# big-GEMM K-loop: per-MFMA-cluster s_setprio 1/0 flips removed, one static s_setprio 1 for waves 4-7 for the whole GEMM phase (reset at phase end)
# speedup vs baseline: 1.0155x; 1.0040x over previous
; #define PG8_STAGE(bufoff, gbase, voff) do { _Pragma("unroll") for (int _i = 0; _i < 2; ++_i) \
;         __builtin_amdgcn_global_load_lds((const unsigned*)((const char*)(gbase) + (voff)[_i]), (PG8_LAS unsigned*)(lds + (bufoff) + ldsw + _i * 8192), 16, 0, 0); } while (0)
; #define PG8_WAIT_V(n) asm volatile("s_waitcnt vmcnt(" #n ")" ::: "memory")
; #define PG8_BAR __builtin_amdgcn_s_barrier()
; template <class Epi, class Sched, bool STAMP = false>
; __device__ __forceinline__ void gemm_phase(PG8_LAS unsigned char* lds, const Gemm g, const Sched& S, const Epi& E, unsigned long long* stamps) {
;     ...
;     const char* cA = (const char*)g.A + (size_t)cur.pm * tstep; const char* cB = (const char*)g.Bt + (size_t)cur.pn * tstep;
;     S.a_ready(cur);
;     PG8_STAGE(PG8_SB(0, 0), cB, voffB); PG8_STAGE(PG8_SA(0, 0), cA, voffA); PG8_STAGE(PG8_SB(0, 1), cB + hstep, voffB); PG8_STAGE(PG8_SA(0, 1), cA + hstep, voffA);
;     if (wr == 1) PG8_BAR;
;     PG8_WAIT_V(4); PG8_BAR;
;     PG8_STAGE(PG8_SB(1, 0), cB + kstep, voffB); PG8_STAGE(PG8_SA(1, 0), cA + kstep, voffA); PG8_STAGE(PG8_SB(1, 1), cB + hstep + kstep, voffB);
;     PG8_WAIT_V(6); PG8_BAR;
;     for (;;) {
;         const bool has_next = S.next(ui + 1, nxt);
.LBB0_736:
	v_mov_b32_e32 v165, v0
	v_lshrrev_b32_e32 v22, 1, v9
	v_lshl_add_u64 v[10:11], s[88:89], 0, v[164:165]
	v_mov_b32_e32 v171, v0
	v_and_b32_e32 v216, 24, v22
	v_lshl_add_u64 v[12:13], s[88:89], 0, v[170:171]
	v_mov_b32_e32 v163, v0
	v_and_b32_e32 v1, 15, v9
	v_lshlrev_b32_e32 v22, 1, v216
	v_lshlrev_b32_e32 v9, 2, v9
	s_add_i32 m0, s80, 0x18000
	v_lshl_add_u64 v[10:11], v[10:11], 0, s[10:11]
	v_lshl_add_u64 v[14:15], s[22:23], 0, v[162:163]
	v_mov_b32_e32 v167, v0
	v_lshl_add_u64 v[18:19], s[0:1], 0, v[164:165]
	v_lshl_add_u64 v[20:21], s[0:1], 0, v[170:171]
	v_lshl_or_b32 v22, v1, 6, v22
	s_lshl_b32 s0, s30, 13
	v_and_b32_e32 v9, 32, v9
	s_waitcnt vmcnt(4)
	s_barrier
	global_load_lds_dwordx4 v[10:11], off
	v_lshl_add_u64 v[10:11], v[12:13], 0, s[10:11]
	s_add_i32 m0, s80, 0x1a000
	s_add_i32 s33, s80, 0x8000
	v_lshl_add_u64 v[16:17], s[22:23], 0, v[166:167]
	v_bitop3_b32 v23, v22, s0, v9 bitop3:0xde
	s_lshl_b32 s0, s28, 5
	global_load_lds_dwordx4 v[10:11], off
	v_lshl_add_u64 v[10:11], v[14:15], 0, s[10:11]
	s_mov_b32 m0, s33
	s_add_i32 s28, s80, 0xa000
	global_load_lds_dwordx4 v[10:11], off
	v_lshl_add_u64 v[10:11], v[16:17], 0, s[10:11]
	s_mov_b32 m0, s28
	v_rcp_iflag_f32_e32 v2, v2
	global_load_lds_dwordx4 v[10:11], off
	s_add_i32 m0, s80, 0x1c000
	v_lshl_add_u64 v[10:11], v[18:19], 0, s[10:11]
	global_load_lds_dwordx4 v[10:11], off
	v_lshl_add_u64 v[10:11], v[20:21], 0, s[10:11]
	s_add_i32 m0, s80, 0x1e000
	v_mul_f32_e32 v2, 0x4f7ffffe, v2
	global_load_lds_dwordx4 v[10:11], off
	v_cvt_u32_f32_e32 v2, v2
	s_and_b32 s72, s0, 0x60
	s_lshl_b32 s0, s72, 7
	v_bitop3_b32 v217, v22, s0, v9 bitop3:0xde
	v_readfirstlane_b32 s1, v2
	v_add_u32_e32 v2, v5, v3
	s_sub_i32 s0, 0, s73
	v_add_lshl_u32 v2, v2, v4, 1
	v_mov_b32_e32 v3, v0
	s_waitcnt vmcnt(6)
	s_mul_i32 s0, s0, s1
	v_lshl_add_u64 v[172:173], s[94:95], 0, v[2:3]
	v_add_u32_e32 v2, v8, v6
	s_lshr_b32 s26, s4, 6
	s_mul_hi_u32 s0, s1, s0
	v_add_lshl_u32 v2, v2, v7, 1
	s_lshl_b32 s5, s30, 6
	s_add_i32 s4, s26, -2
	s_mov_b32 s69, s95
	s_lshr_b32 s34, s68, 3
	s_mov_b32 s70, 0
	s_add_i32 s71, s1, s0
	v_lshl_add_u64 v[174:175], s[94:95], 0, v[2:3]
	v_add_u32_e32 v218, 0, v23
	v_readfirstlane_b32 s98, v169
	s_cmpk_lt_u32 s98, 0x100
	s_cbranch_scc1 .Lg_prio_skip
	s_setprio 1
.Lg_prio_skip:
	s_barrier
	s_branch .LBB0_738

; #define PG8_STAGE(bufoff, gbase, voff) do { _Pragma("unroll") for (int _i = 0; _i < 2; ++_i) \
;         __builtin_amdgcn_global_load_lds((const unsigned*)((const char*)(gbase) + (voff)[_i]), (PG8_LAS unsigned*)(lds + (bufoff) + ldsw + _i * 8192), 16, 0, 0); } while (0)
; #define PG8_LDA(dst, b, h) do { _Pragma("unroll") for (int m = 0; m < 4; ++m) _Pragma("unroll") for (int k = 0; k < 2; ++k) dst[m][k] = *(const PG8_LAS bf16x8*)(lds + PG8_SA(b, h) + aoff + m * 2048 + k * 1024); } while (0)
; #define PG8_LDB(dst, b, h) do { _Pragma("unroll") for (int n = 0; n < 2; ++n) _Pragma("unroll") for (int k = 0; k < 2; ++k) dst[n][k] = *(const PG8_LAS bf16x8*)(lds + PG8_SB(b, h) + boff + n * 2048 + k * 1024); } while (0)
; #define PG8_MMA(ai, bj, At, Bt) do { __builtin_amdgcn_s_setprio(1); _Pragma("unroll") for (int m = 0; m < 4; ++m) _Pragma("unroll") for (int n = 0; n < 2; ++n) _Pragma("unroll") for (int k = 0; k < 2; ++k) \
;         acc[ai][bj][m][n] = __builtin_amdgcn_mfma_f32_16x16x32_bf16(Bt[n][k], At[m][k], acc[ai][bj][m][n], 0, 0, 0); __builtin_amdgcn_s_setprio(0); } while (0)
; #define PG8_WAIT_V(n) asm volatile("s_waitcnt vmcnt(" #n ")" ::: "memory")
; #define PG8_WAIT_L(n) asm volatile("s_waitcnt lgkmcnt(" #n ")" ::: "memory")
; #define PG8_BAR __builtin_amdgcn_s_barrier()
; #define PG8_SCHED __builtin_amdgcn_sched_barrier(0)
; template <class Epi, class Sched, bool STAMP = false>
; __device__ __forceinline__ void gemm_phase(PG8_LAS unsigned char* lds, const Gemm g, const Sched& S, const Epi& E, unsigned long long* stamps) {
;     ...
;             PG8_LDB(B0, 0, 0); PG8_SCHED; PG8_LDA(At, 0, 0); PG8_STAGE(PG8_SA(1, 1), a1 + hstep, voffA);
;             PG8_WAIT_L(8); PG8_BAR; PG8_WAIT_L(0); PG8_MMA(0, 0, At, B0); PG8_BAR; PG8_SCHED;
;             PG8_LDB(B1, 0, 1); PG8_STAGE(PG8_SB(0, 0), b2, voffB);
;             PG8_BAR; PG8_WAIT_L(0); PG8_MMA(0, 1, At, B1); PG8_BAR;
;             PG8_LDA(At, 0, 1); PG8_STAGE(PG8_SA(0, 0), a2, voffA);
;             PG8_BAR; PG8_WAIT_L(0); PG8_MMA(1, 0, At, B0); PG8_BAR; PG8_SCHED;
;             PG8_STAGE(PG8_SB(0, 1), b2 + hstep, voffB);
;             PG8_WAIT_V(6); PG8_BAR; PG8_MMA(1, 1, At, B1); PG8_BAR;
.LBB0_745:
	s_add_i32 s93, s22, 2
	s_add_u32 s38, s0, 0x80
	s_addc_u32 s23, s1, 0
	s_add_i32 s62, 0, 0x10000
	v_add_u32_e32 v142, s62, v217
	ds_read_b128 v[130:133], v142
	ds_read_b128 v[134:137], v142 offset:1024
	ds_read_b128 v[138:141], v142 offset:2048
	ds_read_b128 v[142:145], v142 offset:3072
	s_cmp_eq_u32 s4, s22
	s_cselect_b32 s22, s90, s38
	s_cselect_b32 s23, s91, s23
	s_cselect_b32 s39, s31, s89
	s_cselect_b32 s38, s30, s88
	v_lshl_add_u64 v[192:193], s[0:1], 0, v[172:173]
	s_add_i32 m0, s80, 0xc000
	ds_read_b128 v[146:149], v218
	ds_read_b128 v[150:153], v218 offset:1024
	ds_read_b128 v[154:157], v218 offset:2048
	ds_read_b128 v[158:161], v218 offset:3072
	ds_read_b128 v[176:179], v218 offset:4096
	ds_read_b128 v[180:183], v218 offset:5120
	ds_read_b128 v[184:187], v218 offset:6144
	ds_read_b128 v[188:191], v218 offset:7168
	global_load_lds_dwordx4 v[192:193], off
	v_lshl_add_u64 v[192:193], s[0:1], 0, v[174:175]
	s_add_i32 m0, s80, 0xe000
	s_nop 0
	global_load_lds_dwordx4 v[192:193], off
	s_waitcnt lgkmcnt(8)
	s_barrier
	s_waitcnt lgkmcnt(0)
	s_waitcnt lgkmcnt(0)
	v_mfma_f32_16x16x32_bf16 v[126:129], v[130:133], v[146:149], v[126:129]
	v_mfma_f32_16x16x32_bf16 v[122:125], v[138:141], v[146:149], v[122:125]
	v_mfma_f32_16x16x32_bf16 v[118:121], v[130:133], v[154:157], v[118:121]
	v_mfma_f32_16x16x32_bf16 v[114:117], v[138:141], v[154:157], v[114:117]
	v_mfma_f32_16x16x32_bf16 v[102:105], v[130:133], v[176:179], v[102:105]
	v_mfma_f32_16x16x32_bf16 v[98:101], v[138:141], v[176:179], v[98:101]
	v_mfma_f32_16x16x32_bf16 v[86:89], v[130:133], v[184:187], v[86:89]
	v_mfma_f32_16x16x32_bf16 v[82:85], v[138:141], v[184:187], v[82:85]
	v_mfma_f32_16x16x32_bf16 v[126:129], v[134:137], v[150:153], v[126:129]
	v_mfma_f32_16x16x32_bf16 v[122:125], v[142:145], v[150:153], v[122:125]
	v_mfma_f32_16x16x32_bf16 v[118:121], v[134:137], v[158:161], v[118:121]
	v_mfma_f32_16x16x32_bf16 v[114:117], v[142:145], v[158:161], v[114:117]
	v_mfma_f32_16x16x32_bf16 v[102:105], v[134:137], v[180:183], v[102:105]
	v_mfma_f32_16x16x32_bf16 v[98:101], v[142:145], v[180:183], v[98:101]
	v_mfma_f32_16x16x32_bf16 v[86:89], v[134:137], v[188:191], v[86:89]
	v_mfma_f32_16x16x32_bf16 v[82:85], v[142:145], v[188:191], v[82:85]
	s_barrier
	s_add_i32 s63, 0, 0x14000
	s_add_i32 s62, s62, s79
	v_add_u32_e32 v204, s63, v217
	v_lshl_add_u64 v[208:209], s[38:39], 0, v[164:165]
	s_mov_b32 m0, s62
	ds_read_b128 v[192:195], v204
	ds_read_b128 v[196:199], v204 offset:1024
	ds_read_b128 v[200:203], v204 offset:2048
	ds_read_b128 v[204:207], v204 offset:3072
	global_load_lds_dwordx4 v[208:209], off
	v_lshl_add_u64 v[220:221], s[38:39], 0, v[170:171]
	s_add_i32 m0, s62, 0x2000
	s_nop 0
	global_load_lds_dwordx4 v[220:221], off
	s_barrier
	s_waitcnt lgkmcnt(0)
	s_waitcnt lgkmcnt(0)
	v_mfma_f32_16x16x32_bf16 v[110:113], v[192:195], v[146:149], v[110:113]
	v_mfma_f32_16x16x32_bf16 v[106:109], v[200:203], v[146:149], v[106:109]
	v_mfma_f32_16x16x32_bf16 v[94:97], v[192:195], v[154:157], v[94:97]
	v_mfma_f32_16x16x32_bf16 v[90:93], v[200:203], v[154:157], v[90:93]
	v_mfma_f32_16x16x32_bf16 v[78:81], v[192:195], v[176:179], v[78:81]
	v_mfma_f32_16x16x32_bf16 v[74:77], v[200:203], v[176:179], v[74:77]
	v_mfma_f32_16x16x32_bf16 v[70:73], v[192:195], v[184:187], v[70:73]
	v_mfma_f32_16x16x32_bf16 v[66:69], v[200:203], v[184:187], v[66:69]
	v_mfma_f32_16x16x32_bf16 v[110:113], v[196:199], v[150:153], v[110:113]
	v_mfma_f32_16x16x32_bf16 v[106:109], v[204:207], v[150:153], v[106:109]
	v_mfma_f32_16x16x32_bf16 v[94:97], v[196:199], v[158:161], v[94:97]
	v_mfma_f32_16x16x32_bf16 v[90:93], v[204:207], v[158:161], v[90:93]
	v_mfma_f32_16x16x32_bf16 v[78:81], v[196:199], v[180:183], v[78:81]
	v_mfma_f32_16x16x32_bf16 v[74:77], v[204:207], v[180:183], v[74:77]
	v_mfma_f32_16x16x32_bf16 v[70:73], v[196:199], v[188:191], v[70:73]
	v_mfma_f32_16x16x32_bf16 v[66:69], v[204:207], v[188:191], v[66:69]
	s_mov_b32 m0, s80
	v_lshl_add_u64 v[222:223], s[22:23], 0, v[162:163]
	s_barrier
	ds_read_b128 v[146:149], v218 offset:16384
	ds_read_b128 v[150:153], v218 offset:17408
	ds_read_b128 v[154:157], v218 offset:18432
	ds_read_b128 v[158:161], v218 offset:19456
	ds_read_b128 v[176:179], v218 offset:20480
	ds_read_b128 v[180:183], v218 offset:21504
	ds_read_b128 v[184:187], v218 offset:22528
	ds_read_b128 v[188:191], v218 offset:23552
	global_load_lds_dwordx4 v[222:223], off
	v_lshl_add_u64 v[224:225], s[22:23], 0, v[166:167]
	s_mov_b32 m0, s81
	s_nop 0
	global_load_lds_dwordx4 v[224:225], off
	s_barrier
	s_waitcnt lgkmcnt(0)
	s_waitcnt lgkmcnt(0)
	v_mfma_f32_16x16x32_bf16 v[62:65], v[130:133], v[146:149], v[62:65]
	v_mfma_f32_16x16x32_bf16 v[58:61], v[138:141], v[146:149], v[58:61]
	v_mfma_f32_16x16x32_bf16 v[54:57], v[130:133], v[154:157], v[54:57]
	v_mfma_f32_16x16x32_bf16 v[50:53], v[138:141], v[154:157], v[50:53]
	v_mfma_f32_16x16x32_bf16 v[38:41], v[130:133], v[176:179], v[38:41]
	v_mfma_f32_16x16x32_bf16 v[34:37], v[138:141], v[176:179], v[34:37]
	v_mfma_f32_16x16x32_bf16 v[22:25], v[130:133], v[184:187], v[22:25]
	v_mfma_f32_16x16x32_bf16 v[18:21], v[138:141], v[184:187], v[18:21]
	v_mfma_f32_16x16x32_bf16 v[62:65], v[134:137], v[150:153], v[62:65]
	v_mfma_f32_16x16x32_bf16 v[58:61], v[142:145], v[150:153], v[58:61]
	v_mfma_f32_16x16x32_bf16 v[54:57], v[134:137], v[158:161], v[54:57]
	v_mfma_f32_16x16x32_bf16 v[50:53], v[142:145], v[158:161], v[50:53]
	v_mfma_f32_16x16x32_bf16 v[38:41], v[134:137], v[180:183], v[38:41]
	v_mfma_f32_16x16x32_bf16 v[34:37], v[142:145], v[180:183], v[34:37]
	v_mfma_f32_16x16x32_bf16 v[22:25], v[134:137], v[188:191], v[22:25]
	v_mfma_f32_16x16x32_bf16 v[18:21], v[142:145], v[188:191], v[18:21]
	s_barrier
; #define PG8_STAGE(bufoff, gbase, voff) do { _Pragma("unroll") for (int _i = 0; _i < 2; ++_i) \
;         __builtin_amdgcn_global_load_lds((const unsigned*)((const char*)(gbase) + (voff)[_i]), (PG8_LAS unsigned*)(lds + (bufoff) + ldsw + _i * 8192), 16, 0, 0); } while (0)
; #define PG8_LDA(dst, b, h) do { _Pragma("unroll") for (int m = 0; m < 4; ++m) _Pragma("unroll") for (int k = 0; k < 2; ++k) dst[m][k] = *(const PG8_LAS bf16x8*)(lds + PG8_SA(b, h) + aoff + m * 2048 + k * 1024); } while (0)
; #define PG8_LDB(dst, b, h) do { _Pragma("unroll") for (int n = 0; n < 2; ++n) _Pragma("unroll") for (int k = 0; k < 2; ++k) dst[n][k] = *(const PG8_LAS bf16x8*)(lds + PG8_SB(b, h) + boff + n * 2048 + k * 1024); } while (0)
; #define PG8_MMA(ai, bj, At, Bt) do { __builtin_amdgcn_s_setprio(1); _Pragma("unroll") for (int m = 0; m < 4; ++m) _Pragma("unroll") for (int n = 0; n < 2; ++n) _Pragma("unroll") for (int k = 0; k < 2; ++k) \
;         acc[ai][bj][m][n] = __builtin_amdgcn_mfma_f32_16x16x32_bf16(Bt[n][k], At[m][k], acc[ai][bj][m][n], 0, 0, 0); __builtin_amdgcn_s_setprio(0); } while (0)
; #define PG8_WAIT_V(n) asm volatile("s_waitcnt vmcnt(" #n ")" ::: "memory")
; #define PG8_WAIT_L(n) asm volatile("s_waitcnt lgkmcnt(" #n ")" ::: "memory")
; #define PG8_BAR __builtin_amdgcn_s_barrier()
; #define PG8_SCHED __builtin_amdgcn_sched_barrier(0)
; template <class Epi, class Sched, bool STAMP = false>
; __device__ __forceinline__ void gemm_phase(PG8_LAS unsigned char* lds, const Gemm g, const Sched& S, const Epi& E, unsigned long long* stamps) {
;     ...
;             PG8_WAIT_V(6); PG8_BAR; PG8_MMA(1, 1, At, B1); PG8_BAR;
;             PG8_LDB(B0, 1, 0); PG8_SCHED; PG8_LDA(At, 1, 0); PG8_STAGE(PG8_SA(0, 1), a2 + hstep, voffA);
;             PG8_WAIT_L(8); PG8_BAR; PG8_WAIT_L(0); PG8_MMA(0, 0, At, B0); PG8_BAR; PG8_SCHED;
;             PG8_LDB(B1, 1, 1); PG8_STAGE(PG8_SB(1, 0), b3, voffB);
;             PG8_BAR; PG8_WAIT_L(0); PG8_MMA(0, 1, At, B1); PG8_BAR;
;             PG8_LDA(At, 1, 1); PG8_STAGE(PG8_SA(1, 0), a3, voffA);
;             PG8_BAR; PG8_WAIT_L(0); PG8_MMA(1, 0, At, B0); PG8_BAR; PG8_SCHED;
	s_add_u32 s38, s38, s94
	s_addc_u32 s39, s39, 0
	s_add_i32 s62, s63, s79
	v_lshl_add_u64 v[226:227], s[38:39], 0, v[164:165]
	s_mov_b32 m0, s62
	v_lshl_add_u64 v[228:229], s[38:39], 0, v[170:171]
	global_load_lds_dwordx4 v[226:227], off
	s_add_i32 m0, s62, 0x2000
	s_nop 0
	global_load_lds_dwordx4 v[228:229], off
	s_waitcnt vmcnt(6)
	s_barrier
	v_mfma_f32_16x16x32_bf16 v[46:49], v[192:195], v[146:149], v[46:49]
	v_mfma_f32_16x16x32_bf16 v[42:45], v[200:203], v[146:149], v[42:45]
	v_mfma_f32_16x16x32_bf16 v[30:33], v[192:195], v[154:157], v[30:33]
	v_mfma_f32_16x16x32_bf16 v[26:29], v[200:203], v[154:157], v[26:29]
	v_mfma_f32_16x16x32_bf16 v[14:17], v[192:195], v[176:179], v[14:17]
	v_mfma_f32_16x16x32_bf16 v[10:13], v[200:203], v[176:179], v[10:13]
	v_mfma_f32_16x16x32_bf16 v[6:9], v[192:195], v[184:187], v[6:9]
	v_mfma_f32_16x16x32_bf16 v[2:5], v[200:203], v[184:187], v[2:5]
	v_mfma_f32_16x16x32_bf16 v[46:49], v[196:199], v[150:153], v[46:49]
	v_mfma_f32_16x16x32_bf16 v[42:45], v[204:207], v[150:153], v[42:45]
	v_mfma_f32_16x16x32_bf16 v[30:33], v[196:199], v[158:161], v[30:33]
	v_mfma_f32_16x16x32_bf16 v[26:29], v[204:207], v[158:161], v[26:29]
	v_mfma_f32_16x16x32_bf16 v[14:17], v[196:199], v[180:183], v[14:17]
	v_mfma_f32_16x16x32_bf16 v[10:13], v[204:207], v[180:183], v[10:13]
	v_mfma_f32_16x16x32_bf16 v[6:9], v[196:199], v[188:191], v[6:9]
	v_mfma_f32_16x16x32_bf16 v[2:5], v[204:207], v[188:191], v[2:5]
	s_add_i32 s38, 0, 0x18000
	v_add_u32_e32 v142, s38, v217
	s_barrier
	ds_read_b128 v[130:133], v142
	ds_read_b128 v[134:137], v142 offset:1024
	ds_read_b128 v[138:141], v142 offset:2048
	ds_read_b128 v[142:145], v142 offset:3072
	s_add_u32 s22, s22, s94
	s_addc_u32 s23, s23, 0
	s_mov_b32 m0, s84
	v_lshl_add_u64 v[192:193], s[22:23], 0, v[162:163]
	ds_read_b128 v[146:149], v218 offset:32768
	ds_read_b128 v[150:153], v218 offset:33792
	ds_read_b128 v[154:157], v218 offset:34816
	ds_read_b128 v[158:161], v218 offset:35840
	ds_read_b128 v[176:179], v218 offset:36864
	ds_read_b128 v[180:183], v218 offset:37888
	ds_read_b128 v[184:187], v218 offset:38912
	ds_read_b128 v[188:191], v218 offset:39936
	global_load_lds_dwordx4 v[192:193], off
	v_lshl_add_u64 v[192:193], s[22:23], 0, v[166:167]
	s_mov_b32 m0, s85
	s_nop 0
	global_load_lds_dwordx4 v[192:193], off
	s_waitcnt lgkmcnt(8)
	s_barrier
	s_waitcnt lgkmcnt(0)
	s_waitcnt lgkmcnt(0)
	v_mfma_f32_16x16x32_bf16 v[126:129], v[130:133], v[146:149], v[126:129]
	v_mfma_f32_16x16x32_bf16 v[122:125], v[138:141], v[146:149], v[122:125]
	v_mfma_f32_16x16x32_bf16 v[118:121], v[130:133], v[154:157], v[118:121]
	v_mfma_f32_16x16x32_bf16 v[114:117], v[138:141], v[154:157], v[114:117]
	v_mfma_f32_16x16x32_bf16 v[102:105], v[130:133], v[176:179], v[102:105]
	v_mfma_f32_16x16x32_bf16 v[98:101], v[138:141], v[176:179], v[98:101]
	v_mfma_f32_16x16x32_bf16 v[86:89], v[130:133], v[184:187], v[86:89]
	v_mfma_f32_16x16x32_bf16 v[82:85], v[138:141], v[184:187], v[82:85]
	v_mfma_f32_16x16x32_bf16 v[126:129], v[134:137], v[150:153], v[126:129]
	v_mfma_f32_16x16x32_bf16 v[122:125], v[142:145], v[150:153], v[122:125]
	v_mfma_f32_16x16x32_bf16 v[118:121], v[134:137], v[158:161], v[118:121]
	v_mfma_f32_16x16x32_bf16 v[114:117], v[142:145], v[158:161], v[114:117]
	v_mfma_f32_16x16x32_bf16 v[102:105], v[134:137], v[180:183], v[102:105]
	v_mfma_f32_16x16x32_bf16 v[98:101], v[142:145], v[180:183], v[98:101]
	v_mfma_f32_16x16x32_bf16 v[86:89], v[134:137], v[188:191], v[86:89]
	v_mfma_f32_16x16x32_bf16 v[82:85], v[142:145], v[188:191], v[82:85]
	s_barrier
	s_add_i32 s22, s38, s79
	v_add_u32_e32 v204, s35, v217
	v_lshl_add_u64 v[208:209], v[208:209], 0, s[10:11]
	s_mov_b32 m0, s22
	ds_read_b128 v[192:195], v204
	ds_read_b128 v[196:199], v204 offset:1024
	ds_read_b128 v[200:203], v204 offset:2048
	ds_read_b128 v[204:207], v204 offset:3072
	global_load_lds_dwordx4 v[208:209], off
	v_lshl_add_u64 v[208:209], v[220:221], 0, s[10:11]
	s_add_i32 m0, s22, 0x2000
	s_nop 0
	global_load_lds_dwordx4 v[208:209], off
	s_barrier
	s_waitcnt lgkmcnt(0)
	s_waitcnt lgkmcnt(0)
	v_mfma_f32_16x16x32_bf16 v[110:113], v[192:195], v[146:149], v[110:113]
	v_mfma_f32_16x16x32_bf16 v[106:109], v[200:203], v[146:149], v[106:109]
	v_mfma_f32_16x16x32_bf16 v[94:97], v[192:195], v[154:157], v[94:97]
	v_mfma_f32_16x16x32_bf16 v[90:93], v[200:203], v[154:157], v[90:93]
	v_mfma_f32_16x16x32_bf16 v[78:81], v[192:195], v[176:179], v[78:81]
	v_mfma_f32_16x16x32_bf16 v[74:77], v[200:203], v[176:179], v[74:77]
	v_mfma_f32_16x16x32_bf16 v[70:73], v[192:195], v[184:187], v[70:73]
	v_mfma_f32_16x16x32_bf16 v[66:69], v[200:203], v[184:187], v[66:69]
	v_mfma_f32_16x16x32_bf16 v[110:113], v[196:199], v[150:153], v[110:113]
	v_mfma_f32_16x16x32_bf16 v[106:109], v[204:207], v[150:153], v[106:109]
	v_mfma_f32_16x16x32_bf16 v[94:97], v[196:199], v[158:161], v[94:97]
	v_mfma_f32_16x16x32_bf16 v[90:93], v[204:207], v[158:161], v[90:93]
	v_mfma_f32_16x16x32_bf16 v[78:81], v[196:199], v[180:183], v[78:81]
	v_mfma_f32_16x16x32_bf16 v[74:77], v[204:207], v[180:183], v[74:77]
	v_mfma_f32_16x16x32_bf16 v[70:73], v[196:199], v[188:191], v[70:73]
	v_mfma_f32_16x16x32_bf16 v[66:69], v[204:207], v[188:191], v[66:69]
	s_mov_b32 m0, s33
	v_lshl_add_u64 v[208:209], v[222:223], 0, s[10:11]
	s_barrier
	ds_read_b128 v[146:149], v218 offset:49152
	ds_read_b128 v[150:153], v218 offset:50176
	ds_read_b128 v[154:157], v218 offset:51200
	ds_read_b128 v[158:161], v218 offset:52224
	ds_read_b128 v[176:179], v218 offset:53248
	ds_read_b128 v[180:183], v218 offset:54272
	ds_read_b128 v[184:187], v218 offset:55296
	ds_read_b128 v[188:191], v218 offset:56320
	global_load_lds_dwordx4 v[208:209], off
	v_lshl_add_u64 v[208:209], v[224:225], 0, s[10:11]
	s_mov_b32 m0, s28
	s_nop 0
	global_load_lds_dwordx4 v[208:209], off
	s_barrier
; DI float sigmoidf_(float x) { return __builtin_amdgcn_rcpf(1.f + __builtin_amdgcn_exp2f(-1.4426950408889634f * x)); }
; #define PG8_STAGE(bufoff, gbase, voff) do { _Pragma("unroll") for (int _i = 0; _i < 2; ++_i) \
;         __builtin_amdgcn_global_load_lds((const unsigned*)((const char*)(gbase) + (voff)[_i]), (PG8_LAS unsigned*)(lds + (bufoff) + ldsw + _i * 8192), 16, 0, 0); } while (0)
; #define PG8_MMA(ai, bj, At, Bt) do { __builtin_amdgcn_s_setprio(1); _Pragma("unroll") for (int m = 0; m < 4; ++m) _Pragma("unroll") for (int n = 0; n < 2; ++n) _Pragma("unroll") for (int k = 0; k < 2; ++k) \
;         acc[ai][bj][m][n] = __builtin_amdgcn_mfma_f32_16x16x32_bf16(Bt[n][k], At[m][k], acc[ai][bj][m][n], 0, 0, 0); __builtin_amdgcn_s_setprio(0); } while (0)
; #define PG8_WAIT_V(n) asm volatile("s_waitcnt vmcnt(" #n ")" ::: "memory")
; #define PG8_WAIT_L(n) asm volatile("s_waitcnt lgkmcnt(" #n ")" ::: "memory")
; #define PG8_BAR __builtin_amdgcn_s_barrier()
; #define PG8_SCHED __builtin_amdgcn_sched_barrier(0)
; template <class Epi, class Sched, bool STAMP = false>
; __device__ __forceinline__ void gemm_phase(PG8_LAS unsigned char* lds, const Gemm g, const Sched& S, const Epi& E, unsigned long long* stamps) {
;     ...
;             PG8_BAR; PG8_WAIT_L(0); PG8_MMA(1, 0, At, B0); PG8_BAR; PG8_SCHED;
;             PG8_STAGE(PG8_SB(1, 1), b3 + hstep, voffB);
;             PG8_WAIT_V(6); PG8_BAR; PG8_MMA(1, 1, At, B1); PG8_BAR;
; DI void conv_phase(const Params& p, int l) {
;     ...
;     const u16* gp = G + (size_t)t0 * DFF + c0;
;     const int s0 = t0 & (S - 1);
;     uint4 rows[RUN + 2];
;     const uint4 z = make_uint4(0, 0, 0, 0);
;     rows[0] = (s0 > 0) ? *(const uint4*)(gp - DFF) : z;
; #pragma unroll
;     for (int i = 0; i < RUN; ++i) rows[i + 1] = *(const uint4*)(gp + (size_t)i * DFF);
;     rows[RUN + 1] = (s0 + RUN - 1 < S - 1) ? *(const uint4*)(gp + (size_t)RUN * DFF) : z;
;     float w0[8], w1[8], w2[8], bb[8];
;     load8f(cw + c0, w0); load8f(cw + DFF + c0, w1); load8f(cw + 2 * DFF + c0, w2); load8f(cb + c0, bb);
;     float prev[8], cur[8], nxt[8];
;     unpack8(rows[0], prev); unpack8(rows[1], cur);
; #pragma unroll
;     for (int i = 0; i < RUN; ++i) {
;       unpack8(rows[i + 2], nxt);
;       float o[8];
; #pragma unroll
;       for (int j = 0; j < 8; ++j) { const float g = w0[j] * prev[j] + w1[j] * cur[j] + w2[j] * nxt[j] + bb[j]; o[j] = g * sigmoidf_(g); }
	s_waitcnt lgkmcnt(0)
	s_waitcnt lgkmcnt(0)
	v_mfma_f32_16x16x32_bf16 v[62:65], v[130:133], v[146:149], v[62:65]
	v_mfma_f32_16x16x32_bf16 v[58:61], v[138:141], v[146:149], v[58:61]
	v_mfma_f32_16x16x32_bf16 v[54:57], v[130:133], v[154:157], v[54:57]
	v_mfma_f32_16x16x32_bf16 v[50:53], v[138:141], v[154:157], v[50:53]
	v_mfma_f32_16x16x32_bf16 v[38:41], v[130:133], v[176:179], v[38:41]
	v_mfma_f32_16x16x32_bf16 v[34:37], v[138:141], v[176:179], v[34:37]
	v_mfma_f32_16x16x32_bf16 v[22:25], v[130:133], v[184:187], v[22:25]
	v_mfma_f32_16x16x32_bf16 v[18:21], v[138:141], v[184:187], v[18:21]
	v_mfma_f32_16x16x32_bf16 v[62:65], v[134:137], v[150:153], v[62:65]
	v_mfma_f32_16x16x32_bf16 v[58:61], v[142:145], v[150:153], v[58:61]
	v_mfma_f32_16x16x32_bf16 v[54:57], v[134:137], v[158:161], v[54:57]
	v_mfma_f32_16x16x32_bf16 v[50:53], v[142:145], v[158:161], v[50:53]
	v_mfma_f32_16x16x32_bf16 v[38:41], v[134:137], v[180:183], v[38:41]
	v_mfma_f32_16x16x32_bf16 v[34:37], v[142:145], v[180:183], v[34:37]
	v_mfma_f32_16x16x32_bf16 v[22:25], v[134:137], v[188:191], v[22:25]
	v_mfma_f32_16x16x32_bf16 v[18:21], v[142:145], v[188:191], v[18:21]
	s_barrier
	s_add_i32 s22, s35, s79
	v_lshl_add_u64 v[130:131], v[226:227], 0, s[10:11]
	s_mov_b32 m0, s22
	s_nop 0
	global_load_lds_dwordx4 v[130:131], off
	v_lshl_add_u64 v[130:131], v[228:229], 0, s[10:11]
	s_add_i32 m0, s22, 0x2000
	s_nop 0
	global_load_lds_dwordx4 v[130:131], off
	s_waitcnt vmcnt(6)
	s_barrier
	v_mfma_f32_16x16x32_bf16 v[46:49], v[192:195], v[146:149], v[46:49]
	v_mfma_f32_16x16x32_bf16 v[42:45], v[200:203], v[146:149], v[42:45]
	v_mfma_f32_16x16x32_bf16 v[30:33], v[192:195], v[154:157], v[30:33]
	v_mfma_f32_16x16x32_bf16 v[26:29], v[200:203], v[154:157], v[26:29]
	v_mfma_f32_16x16x32_bf16 v[14:17], v[192:195], v[176:179], v[14:17]
	v_mfma_f32_16x16x32_bf16 v[10:13], v[200:203], v[176:179], v[10:13]
	v_mfma_f32_16x16x32_bf16 v[6:9], v[192:195], v[184:187], v[6:9]
	v_mfma_f32_16x16x32_bf16 v[2:5], v[200:203], v[184:187], v[2:5]
	v_mfma_f32_16x16x32_bf16 v[46:49], v[196:199], v[150:153], v[46:49]
	v_mfma_f32_16x16x32_bf16 v[42:45], v[204:207], v[150:153], v[42:45]
	v_mfma_f32_16x16x32_bf16 v[30:33], v[196:199], v[158:161], v[30:33]
	v_mfma_f32_16x16x32_bf16 v[26:29], v[204:207], v[158:161], v[26:29]
	v_mfma_f32_16x16x32_bf16 v[14:17], v[196:199], v[180:183], v[14:17]
	v_mfma_f32_16x16x32_bf16 v[10:13], v[204:207], v[180:183], v[10:13]
	v_mfma_f32_16x16x32_bf16 v[6:9], v[196:199], v[188:191], v[6:9]
	v_mfma_f32_16x16x32_bf16 v[2:5], v[204:207], v[188:191], v[2:5]
	s_add_u32 s0, s0, 0x100
	s_addc_u32 s1, s1, 0
	s_add_u32 s88, s88, 0x100
	s_addc_u32 s89, s89, 0
	s_cmp_ge_u32 s93, s26
	s_mov_b32 s22, s93
	s_barrier
	s_cbranch_scc0 .LBB0_745
	s_lshl_b32 s22, s75, 8
	s_lshl_b32 s0, s97, 8
	s_add_i32 s22, s22, s5
	s_or_b32 s75, s0, s72
	v_or_b32_e32 v176, s22, v1
	v_or_b32_e32 v178, s75, v216
	s_cmp_lt_i32 s77, 2
	s_mov_b64 s[0:1], -1
	s_cbranch_scc1 .LBB0_752
	s_cmp_gt_i32 s77, 2
	s_cbranch_scc0 .LBB0_749
	v_ashrrev_i32_e32 v179, 31, v178
	v_lshlrev_b64 v[180:181], 1, v[178:179]
	v_lshl_add_u64 v[180:181], s[46:47], 0, v[180:181]
	v_add_co_u32_e32 v180, vcc, 0xea000000, v180
	s_nop 1
	v_addc_co_u32_e32 v181, vcc, -1, v181, vcc
	v_lshlrev_b32_e32 v182, 2, v178
	v_readlane_b32 s98, v237, 62
	v_readlane_b32 s100, v238, 0
	v_readlane_b32 s101, v238, 1
	s_mul_i32 s98, s98, 0xab
	s_bfe_u32 s98, s98, 0x6000a
	s_mul_i32 s99, s98, 0x8400
	s_add_u32 s100, s100, s99
	s_addc_u32 s101, s101, 0
	s_nop 3
	global_load_dwordx4 v[130:133], v182, s[100:101] offset:0
	global_load_dwordx4 v[134:137], v182, s[100:101] offset:16
	s_add_u32 s100, s100, 0x2c00
	s_addc_u32 s101, s101, 0
	global_load_dwordx4 v[138:141], v182, s[100:101] offset:0
	global_load_dwordx4 v[142:145], v182, s[100:101] offset:16
	s_add_u32 s100, s100, 0x2c00
	s_addc_u32 s101, s101, 0
	global_load_dwordx4 v[146:149], v182, s[100:101] offset:0
	global_load_dwordx4 v[150:153], v182, s[100:101] offset:16
	v_readlane_b32 s100, v238, 2
	v_readlane_b32 s101, v238, 3
	s_mul_i32 s99, s98, 0x2c00
	s_add_u32 s100, s100, s99
	s_addc_u32 s101, s101, 0
	s_nop 3
	global_load_dwordx4 v[154:157], v182, s[100:101] offset:0
	global_load_dwordx4 v[158:161], v182, s[100:101] offset:16
	s_mov_b32 s98, 0x1600
	s_mov_b32 s99, 0
	s_mov_b32 s100, 0x16000000
	s_mov_b32 s101, 0
	v_add_u32_e32 v183, -1, v176
	v_mad_i64_i32 v[222:223], s[0:1], v183, s14, v[180:181]
	v_lshl_add_u64 v[224:225], v[222:223], 0, s[98:99]
	v_lshl_add_u64 v[226:227], v[224:225], 0, s[98:99]
	v_lshl_add_u64 v[196:197], v[224:225], 0, s[100:101]
	global_load_dwordx4 v[184:187], v[222:223], off
	global_load_dwordx4 v[188:191], v[224:225], off
	global_load_dwordx4 v[192:195], v[226:227], off
	v_add_u32_e32 v183, 0xf, v176
	v_mad_i64_i32 v[222:223], s[0:1], v183, s14, v[180:181]
	v_lshl_add_u64 v[224:225], v[222:223], 0, s[98:99]
	v_lshl_add_u64 v[226:227], v[224:225], 0, s[98:99]
	v_lshl_add_u64 v[220:221], v[224:225], 0, s[100:101]
	global_load_dwordx4 v[198:201], v[222:223], off
	global_load_dwordx4 v[202:205], v[224:225], off
	global_load_dwordx4 v[206:209], v[226:227], off
	s_waitcnt vmcnt(3)
; DI unsigned pack2(float a, float b) { f32x2_t v = {a, b}; bf16x2_t r = __builtin_convertvector(v, bf16x2_t); return __builtin_bit_cast(unsigned, r); }
; DI float lo2f(unsigned u) { return __uint_as_float(u << 16); }
; DI float hi2f(unsigned u) { return __uint_as_float(u & 0xffff0000u); }
; DI float sigmoidf_(float x) { return __builtin_amdgcn_rcpf(1.f + __builtin_amdgcn_exp2f(-1.4426950408889634f * x)); }
;   DI void operator()(const f32x4 (&acc)[2][2][4][2], const pg8::Unit& u, int wr, int wc, int fr, int fq) const {
;     ...
;             const f32x4 v0 = acc[ai][bj][m][0], v1 = acc[ai][bj][m][1];
;             const uint4 g = gs[m][bj];
;             f32x4 q0 = {lo2f(g.x) * v0[0], hi2f(g.x) * v0[1], lo2f(g.y) * v0[2], hi2f(g.y) * v0[3]};
;             f32x4 q1 = {lo2f(g.z) * v1[0], hi2f(g.z) * v1[1], lo2f(g.w) * v1[2], hi2f(g.w) * v1[3]};
;             st8(o0 + (size_t)(row0 + ai * 128 + m * 16) * DFF + col0 + bj * 128, q0, q1);
; DI void conv_phase(const Params& p, int l) {
;     ...
;     rows[0] = (s0 > 0) ? *(const uint4*)(gp - DFF) : z;
; #pragma unroll
;     for (int i = 0; i < RUN; ++i) rows[i + 1] = *(const uint4*)(gp + (size_t)i * DFF);
;     rows[RUN + 1] = (s0 + RUN - 1 < S - 1) ? *(const uint4*)(gp + (size_t)RUN * DFF) : z;
;     float w0[8], w1[8], w2[8], bb[8];
;     load8f(cw + c0, w0); load8f(cw + DFF + c0, w1); load8f(cw + 2 * DFF + c0, w2); load8f(cb + c0, bb);
;     float prev[8], cur[8], nxt[8];
;     unpack8(rows[0], prev); unpack8(rows[1], cur);
; #pragma unroll
;     for (int i = 0; i < RUN; ++i) {
;       unpack8(rows[i + 2], nxt);
;       float o[8];
; #pragma unroll
;       for (int j = 0; j < 8; ++j) { const float g = w0[j] * prev[j] + w1[j] * cur[j] + w2[j] * nxt[j] + bb[j]; o[j] = g * sigmoidf_(g); }
;       uint4 oo; oo.x = pack2(o[0], o[1]); oo.y = pack2(o[2], o[3]); oo.z = pack2(o[4], o[5]); oo.w = pack2(o[6], o[7]);
;       *(uint4*)(GS + (size_t)(t0 + i) * DFF + c0) = oo;
	v_and_b32_e32 v183, 0x1fff, v176
	v_cmp_eq_u32_e32 vcc, 0, v183
	v_cndmask_b32_e64 v184, v184, 0, vcc
	v_cndmask_b32_e64 v185, v185, 0, vcc
	v_cndmask_b32_e64 v186, v186, 0, vcc
	v_cndmask_b32_e64 v187, v187, 0, vcc
	v_lshlrev_b32_e32 v240, 16, v184
	v_and_b32_e32 v241, 0xffff0000, v184
	v_lshlrev_b32_e32 v242, 16, v188
	v_and_b32_e32 v243, 0xffff0000, v188
	v_lshlrev_b32_e32 v252, 16, v192
	v_and_b32_e32 v253, 0xffff0000, v192
	v_fma_f32 v254, v130, v240, v154
	v_fma_f32 v255, v131, v241, v155
	v_fma_f32 v254, v138, v242, v254
	v_fma_f32 v255, v139, v243, v255
	v_fma_f32 v254, v146, v252, v254
	v_fma_f32 v255, v147, v253, v255
	v_mul_f32_e32 v240, 0xbfb8aa3b, v254
	v_mul_f32_e32 v241, 0xbfb8aa3b, v255
	v_exp_f32_e32 v240, v240
	v_exp_f32_e32 v241, v241
	v_add_f32_e32 v240, 1.0, v240
	v_add_f32_e32 v241, 1.0, v241
	v_rcp_f32_e32 v240, v240
	v_rcp_f32_e32 v241, v241
	v_mul_f32_e32 v254, v254, v240
	v_mul_f32_e32 v255, v255, v241
	v_mul_f32_e32 v254, v254, v126
	v_mul_f32_e32 v255, v255, v127
	v_cvt_pk_bf16_f32 v244, v254, v255
	v_lshlrev_b32_e32 v240, 16, v185
	v_and_b32_e32 v241, 0xffff0000, v185
	v_lshlrev_b32_e32 v242, 16, v189
	v_and_b32_e32 v243, 0xffff0000, v189
	v_lshlrev_b32_e32 v252, 16, v193
	v_and_b32_e32 v253, 0xffff0000, v193
	v_fma_f32 v254, v132, v240, v156
	v_fma_f32 v255, v133, v241, v157
	v_fma_f32 v254, v140, v242, v254
	v_fma_f32 v255, v141, v243, v255
	v_fma_f32 v254, v148, v252, v254
	v_fma_f32 v255, v149, v253, v255
	v_mul_f32_e32 v240, 0xbfb8aa3b, v254
	v_mul_f32_e32 v241, 0xbfb8aa3b, v255
	v_exp_f32_e32 v240, v240
	v_exp_f32_e32 v241, v241
	v_add_f32_e32 v240, 1.0, v240
	v_add_f32_e32 v241, 1.0, v241
	v_rcp_f32_e32 v240, v240
	v_rcp_f32_e32 v241, v241
	v_mul_f32_e32 v254, v254, v240
	v_mul_f32_e32 v255, v255, v241
	v_mul_f32_e32 v254, v254, v128
	v_mul_f32_e32 v255, v255, v129
	v_cvt_pk_bf16_f32 v245, v254, v255
	v_lshlrev_b32_e32 v240, 16, v186
	v_and_b32_e32 v241, 0xffff0000, v186
	v_lshlrev_b32_e32 v242, 16, v190
	v_and_b32_e32 v243, 0xffff0000, v190
	v_lshlrev_b32_e32 v252, 16, v194
	v_and_b32_e32 v253, 0xffff0000, v194
	v_fma_f32 v254, v134, v240, v158
	v_fma_f32 v255, v135, v241, v159
	v_fma_f32 v254, v142, v242, v254
	v_fma_f32 v255, v143, v243, v255
	v_fma_f32 v254, v150, v252, v254
	v_fma_f32 v255, v151, v253, v255
	v_mul_f32_e32 v240, 0xbfb8aa3b, v254
	v_mul_f32_e32 v241, 0xbfb8aa3b, v255
	v_exp_f32_e32 v240, v240
	v_exp_f32_e32 v241, v241
	v_add_f32_e32 v240, 1.0, v240
	v_add_f32_e32 v241, 1.0, v241
	v_rcp_f32_e32 v240, v240
	v_rcp_f32_e32 v241, v241
	v_mul_f32_e32 v254, v254, v240
	v_mul_f32_e32 v255, v255, v241
	v_mul_f32_e32 v254, v254, v122
	v_mul_f32_e32 v255, v255, v123
	v_cvt_pk_bf16_f32 v246, v254, v255
	v_lshlrev_b32_e32 v240, 16, v187
	v_and_b32_e32 v241, 0xffff0000, v187
	v_lshlrev_b32_e32 v242, 16, v191
	v_and_b32_e32 v243, 0xffff0000, v191
	v_lshlrev_b32_e32 v252, 16, v195
	v_and_b32_e32 v253, 0xffff0000, v195
	v_fma_f32 v254, v136, v240, v160
	v_fma_f32 v255, v137, v241, v161
	v_fma_f32 v254, v144, v242, v254
	v_fma_f32 v255, v145, v243, v255
	v_fma_f32 v254, v152, v252, v254
	v_fma_f32 v255, v153, v253, v255
	v_mul_f32_e32 v240, 0xbfb8aa3b, v254
	v_mul_f32_e32 v241, 0xbfb8aa3b, v255
	v_exp_f32_e32 v240, v240
	v_exp_f32_e32 v241, v241
	v_add_f32_e32 v240, 1.0, v240
	v_add_f32_e32 v241, 1.0, v241
	v_rcp_f32_e32 v240, v240
	v_rcp_f32_e32 v241, v241
	v_mul_f32_e32 v254, v254, v240
	v_mul_f32_e32 v255, v255, v241
	v_mul_f32_e32 v254, v254, v124
	v_mul_f32_e32 v255, v255, v125
	v_cvt_pk_bf16_f32 v247, v254, v255
	global_store_dwordx4 v[196:197], v[244:247], off
	v_add_u32_e32 v183, 0x1f, v176
	v_mad_i64_i32 v[222:223], s[0:1], v183, s14, v[180:181]
	v_lshl_add_u64 v[224:225], v[222:223], 0, s[98:99]
	v_lshl_add_u64 v[226:227], v[224:225], 0, s[98:99]
	v_lshl_add_u64 v[196:197], v[224:225], 0, s[100:101]
	global_load_dwordx4 v[184:187], v[222:223], off
	global_load_dwordx4 v[188:191], v[224:225], off
	global_load_dwordx4 v[192:195], v[226:227], off
	s_waitcnt vmcnt(4)
	v_lshlrev_b32_e32 v240, 16, v198
	v_and_b32_e32 v241, 0xffff0000, v198
	v_lshlrev_b32_e32 v242, 16, v202
	v_and_b32_e32 v243, 0xffff0000, v202
	v_lshlrev_b32_e32 v252, 16, v206
	v_and_b32_e32 v253, 0xffff0000, v206
	v_fma_f32 v254, v130, v240, v154
	v_fma_f32 v255, v131, v241, v155
	v_fma_f32 v254, v138, v242, v254
	v_fma_f32 v255, v139, v243, v255
	v_fma_f32 v254, v146, v252, v254
	v_fma_f32 v255, v147, v253, v255
	v_mul_f32_e32 v240, 0xbfb8aa3b, v254
	v_mul_f32_e32 v241, 0xbfb8aa3b, v255
	v_exp_f32_e32 v240, v240
	v_exp_f32_e32 v241, v241
	v_add_f32_e32 v240, 1.0, v240
	v_add_f32_e32 v241, 1.0, v241
	v_rcp_f32_e32 v240, v240
	v_rcp_f32_e32 v241, v241
	v_mul_f32_e32 v254, v254, v240
	v_mul_f32_e32 v255, v255, v241
	v_mul_f32_e32 v254, v254, v118
	v_mul_f32_e32 v255, v255, v119
	v_cvt_pk_bf16_f32 v248, v254, v255
	v_lshlrev_b32_e32 v240, 16, v199
	v_and_b32_e32 v241, 0xffff0000, v199
	v_lshlrev_b32_e32 v242, 16, v203
	v_and_b32_e32 v243, 0xffff0000, v203
	v_lshlrev_b32_e32 v252, 16, v207
	v_and_b32_e32 v253, 0xffff0000, v207
	v_fma_f32 v254, v132, v240, v156
	v_fma_f32 v255, v133, v241, v157
	v_fma_f32 v254, v140, v242, v254
	v_fma_f32 v255, v141, v243, v255
	v_fma_f32 v254, v148, v252, v254
	v_fma_f32 v255, v149, v253, v255
	v_mul_f32_e32 v240, 0xbfb8aa3b, v254
	v_mul_f32_e32 v241, 0xbfb8aa3b, v255
	v_exp_f32_e32 v240, v240
	v_exp_f32_e32 v241, v241
	v_add_f32_e32 v240, 1.0, v240
	v_add_f32_e32 v241, 1.0, v241
	v_rcp_f32_e32 v240, v240
	v_rcp_f32_e32 v241, v241
	v_mul_f32_e32 v254, v254, v240
	v_mul_f32_e32 v255, v255, v241
	v_mul_f32_e32 v254, v254, v120
	v_mul_f32_e32 v255, v255, v121
	v_cvt_pk_bf16_f32 v249, v254, v255
; DI unsigned pack2(float a, float b) { f32x2_t v = {a, b}; bf16x2_t r = __builtin_convertvector(v, bf16x2_t); return __builtin_bit_cast(unsigned, r); }
; DI float lo2f(unsigned u) { return __uint_as_float(u << 16); }
; DI float hi2f(unsigned u) { return __uint_as_float(u & 0xffff0000u); }
; DI float sigmoidf_(float x) { return __builtin_amdgcn_rcpf(1.f + __builtin_amdgcn_exp2f(-1.4426950408889634f * x)); }
;   DI void operator()(const f32x4 (&acc)[2][2][4][2], const pg8::Unit& u, int wr, int wc, int fr, int fq) const {
;     ...
;             const f32x4 v0 = acc[ai][bj][m][0], v1 = acc[ai][bj][m][1];
;             const uint4 g = gs[m][bj];
;             f32x4 q0 = {lo2f(g.x) * v0[0], hi2f(g.x) * v0[1], lo2f(g.y) * v0[2], hi2f(g.y) * v0[3]};
;             f32x4 q1 = {lo2f(g.z) * v1[0], hi2f(g.z) * v1[1], lo2f(g.w) * v1[2], hi2f(g.w) * v1[3]};
;             st8(o0 + (size_t)(row0 + ai * 128 + m * 16) * DFF + col0 + bj * 128, q0, q1);
; DI void conv_phase(const Params& p, int l) {
;     ...
;     rows[0] = (s0 > 0) ? *(const uint4*)(gp - DFF) : z;
; #pragma unroll
;     for (int i = 0; i < RUN; ++i) rows[i + 1] = *(const uint4*)(gp + (size_t)i * DFF);
;     rows[RUN + 1] = (s0 + RUN - 1 < S - 1) ? *(const uint4*)(gp + (size_t)RUN * DFF) : z;
;     float w0[8], w1[8], w2[8], bb[8];
;     load8f(cw + c0, w0); load8f(cw + DFF + c0, w1); load8f(cw + 2 * DFF + c0, w2); load8f(cb + c0, bb);
;     float prev[8], cur[8], nxt[8];
;     unpack8(rows[0], prev); unpack8(rows[1], cur);
; #pragma unroll
;     for (int i = 0; i < RUN; ++i) {
;       unpack8(rows[i + 2], nxt);
;       float o[8];
; #pragma unroll
;       for (int j = 0; j < 8; ++j) { const float g = w0[j] * prev[j] + w1[j] * cur[j] + w2[j] * nxt[j] + bb[j]; o[j] = g * sigmoidf_(g); }
;       uint4 oo; oo.x = pack2(o[0], o[1]); oo.y = pack2(o[2], o[3]); oo.z = pack2(o[4], o[5]); oo.w = pack2(o[6], o[7]);
;       *(uint4*)(GS + (size_t)(t0 + i) * DFF + c0) = oo;
	v_lshlrev_b32_e32 v240, 16, v200
	v_and_b32_e32 v241, 0xffff0000, v200
	v_lshlrev_b32_e32 v242, 16, v204
	v_and_b32_e32 v243, 0xffff0000, v204
	v_lshlrev_b32_e32 v252, 16, v208
	v_and_b32_e32 v253, 0xffff0000, v208
	v_fma_f32 v254, v134, v240, v158
	v_fma_f32 v255, v135, v241, v159
	v_fma_f32 v254, v142, v242, v254
	v_fma_f32 v255, v143, v243, v255
	v_fma_f32 v254, v150, v252, v254
	v_fma_f32 v255, v151, v253, v255
	v_mul_f32_e32 v240, 0xbfb8aa3b, v254
	v_mul_f32_e32 v241, 0xbfb8aa3b, v255
	v_exp_f32_e32 v240, v240
	v_exp_f32_e32 v241, v241
	v_add_f32_e32 v240, 1.0, v240
	v_add_f32_e32 v241, 1.0, v241
	v_rcp_f32_e32 v240, v240
	v_rcp_f32_e32 v241, v241
	v_mul_f32_e32 v254, v254, v240
	v_mul_f32_e32 v255, v255, v241
	v_mul_f32_e32 v254, v254, v114
	v_mul_f32_e32 v255, v255, v115
	v_cvt_pk_bf16_f32 v250, v254, v255
	v_lshlrev_b32_e32 v240, 16, v201
	v_and_b32_e32 v241, 0xffff0000, v201
	v_lshlrev_b32_e32 v242, 16, v205
	v_and_b32_e32 v243, 0xffff0000, v205
	v_lshlrev_b32_e32 v252, 16, v209
	v_and_b32_e32 v253, 0xffff0000, v209
	v_fma_f32 v254, v136, v240, v160
	v_fma_f32 v255, v137, v241, v161
	v_fma_f32 v254, v144, v242, v254
	v_fma_f32 v255, v145, v243, v255
	v_fma_f32 v254, v152, v252, v254
	v_fma_f32 v255, v153, v253, v255
	v_mul_f32_e32 v240, 0xbfb8aa3b, v254
	v_mul_f32_e32 v241, 0xbfb8aa3b, v255
	v_exp_f32_e32 v240, v240
	v_exp_f32_e32 v241, v241
	v_add_f32_e32 v240, 1.0, v240
	v_add_f32_e32 v241, 1.0, v241
	v_rcp_f32_e32 v240, v240
	v_rcp_f32_e32 v241, v241
	v_mul_f32_e32 v254, v254, v240
	v_mul_f32_e32 v255, v255, v241
	v_mul_f32_e32 v254, v254, v116
	v_mul_f32_e32 v255, v255, v117
	v_cvt_pk_bf16_f32 v251, v254, v255
	global_store_dwordx4 v[220:221], v[248:251], off
	v_add_u32_e32 v183, 0x2f, v176
	v_mad_i64_i32 v[222:223], s[0:1], v183, s14, v[180:181]
	v_lshl_add_u64 v[224:225], v[222:223], 0, s[98:99]
	v_lshl_add_u64 v[226:227], v[224:225], 0, s[98:99]
	v_lshl_add_u64 v[220:221], v[224:225], 0, s[100:101]
	global_load_dwordx4 v[198:201], v[222:223], off
	global_load_dwordx4 v[202:205], v[224:225], off
	global_load_dwordx4 v[206:209], v[226:227], off
	s_waitcnt vmcnt(4)
	v_lshlrev_b32_e32 v240, 16, v184
	v_and_b32_e32 v241, 0xffff0000, v184
	v_lshlrev_b32_e32 v242, 16, v188
	v_and_b32_e32 v243, 0xffff0000, v188
	v_lshlrev_b32_e32 v252, 16, v192
	v_and_b32_e32 v253, 0xffff0000, v192
	v_fma_f32 v254, v130, v240, v154
	v_fma_f32 v255, v131, v241, v155
	v_fma_f32 v254, v138, v242, v254
	v_fma_f32 v255, v139, v243, v255
	v_fma_f32 v254, v146, v252, v254
	v_fma_f32 v255, v147, v253, v255
	v_mul_f32_e32 v240, 0xbfb8aa3b, v254
	v_mul_f32_e32 v241, 0xbfb8aa3b, v255
	v_exp_f32_e32 v240, v240
	v_exp_f32_e32 v241, v241
	v_add_f32_e32 v240, 1.0, v240
	v_add_f32_e32 v241, 1.0, v241
	v_rcp_f32_e32 v240, v240
	v_rcp_f32_e32 v241, v241
	v_mul_f32_e32 v254, v254, v240
	v_mul_f32_e32 v255, v255, v241
	v_mul_f32_e32 v254, v254, v102
	v_mul_f32_e32 v255, v255, v103
	v_cvt_pk_bf16_f32 v244, v254, v255
	v_lshlrev_b32_e32 v240, 16, v185
	v_and_b32_e32 v241, 0xffff0000, v185
	v_lshlrev_b32_e32 v242, 16, v189
	v_and_b32_e32 v243, 0xffff0000, v189
	v_lshlrev_b32_e32 v252, 16, v193
	v_and_b32_e32 v253, 0xffff0000, v193
	v_fma_f32 v254, v132, v240, v156
	v_fma_f32 v255, v133, v241, v157
	v_fma_f32 v254, v140, v242, v254
	v_fma_f32 v255, v141, v243, v255
	v_fma_f32 v254, v148, v252, v254
	v_fma_f32 v255, v149, v253, v255
	v_mul_f32_e32 v240, 0xbfb8aa3b, v254
	v_mul_f32_e32 v241, 0xbfb8aa3b, v255
	v_exp_f32_e32 v240, v240
	v_exp_f32_e32 v241, v241
	v_add_f32_e32 v240, 1.0, v240
	v_add_f32_e32 v241, 1.0, v241
	v_rcp_f32_e32 v240, v240
	v_rcp_f32_e32 v241, v241
	v_mul_f32_e32 v254, v254, v240
	v_mul_f32_e32 v255, v255, v241
	v_mul_f32_e32 v254, v254, v104
	v_mul_f32_e32 v255, v255, v105
	v_cvt_pk_bf16_f32 v245, v254, v255
	v_lshlrev_b32_e32 v240, 16, v186
	v_and_b32_e32 v241, 0xffff0000, v186
	v_lshlrev_b32_e32 v242, 16, v190
	v_and_b32_e32 v243, 0xffff0000, v190
	v_lshlrev_b32_e32 v252, 16, v194
	v_and_b32_e32 v253, 0xffff0000, v194
	v_fma_f32 v254, v134, v240, v158
	v_fma_f32 v255, v135, v241, v159
	v_fma_f32 v254, v142, v242, v254
	v_fma_f32 v255, v143, v243, v255
	v_fma_f32 v254, v150, v252, v254
	v_fma_f32 v255, v151, v253, v255
	v_mul_f32_e32 v240, 0xbfb8aa3b, v254
	v_mul_f32_e32 v241, 0xbfb8aa3b, v255
	v_exp_f32_e32 v240, v240
	v_exp_f32_e32 v241, v241
	v_add_f32_e32 v240, 1.0, v240
	v_add_f32_e32 v241, 1.0, v241
	v_rcp_f32_e32 v240, v240
	v_rcp_f32_e32 v241, v241
	v_mul_f32_e32 v254, v254, v240
	v_mul_f32_e32 v255, v255, v241
	v_mul_f32_e32 v254, v254, v98
	v_mul_f32_e32 v255, v255, v99
	v_cvt_pk_bf16_f32 v246, v254, v255
	v_lshlrev_b32_e32 v240, 16, v187
	v_and_b32_e32 v241, 0xffff0000, v187
	v_lshlrev_b32_e32 v242, 16, v191
	v_and_b32_e32 v243, 0xffff0000, v191
	v_lshlrev_b32_e32 v252, 16, v195
	v_and_b32_e32 v253, 0xffff0000, v195
	v_fma_f32 v254, v136, v240, v160
	v_fma_f32 v255, v137, v241, v161
	v_fma_f32 v254, v144, v242, v254
	v_fma_f32 v255, v145, v243, v255
	v_fma_f32 v254, v152, v252, v254
	v_fma_f32 v255, v153, v253, v255
	v_mul_f32_e32 v240, 0xbfb8aa3b, v254
	v_mul_f32_e32 v241, 0xbfb8aa3b, v255
	v_exp_f32_e32 v240, v240
	v_exp_f32_e32 v241, v241
	v_add_f32_e32 v240, 1.0, v240
	v_add_f32_e32 v241, 1.0, v241
	v_rcp_f32_e32 v240, v240
	v_rcp_f32_e32 v241, v241
	v_mul_f32_e32 v254, v254, v240
	v_mul_f32_e32 v255, v255, v241
	v_mul_f32_e32 v254, v254, v100
	v_mul_f32_e32 v255, v255, v101
	v_cvt_pk_bf16_f32 v247, v254, v255
	global_store_dwordx4 v[196:197], v[244:247], off
	v_add_u32_e32 v183, 0x7f, v176
	v_mad_i64_i32 v[222:223], s[0:1], v183, s14, v[180:181]
	v_lshl_add_u64 v[224:225], v[222:223], 0, s[98:99]
	v_lshl_add_u64 v[226:227], v[224:225], 0, s[98:99]
	v_lshl_add_u64 v[196:197], v[224:225], 0, s[100:101]
	global_load_dwordx4 v[184:187], v[222:223], off
	global_load_dwordx4 v[188:191], v[224:225], off
	global_load_dwordx4 v[192:195], v[226:227], off
	s_waitcnt vmcnt(4)
; DI unsigned pack2(float a, float b) { f32x2_t v = {a, b}; bf16x2_t r = __builtin_convertvector(v, bf16x2_t); return __builtin_bit_cast(unsigned, r); }
; DI float lo2f(unsigned u) { return __uint_as_float(u << 16); }
; DI float hi2f(unsigned u) { return __uint_as_float(u & 0xffff0000u); }
; DI float sigmoidf_(float x) { return __builtin_amdgcn_rcpf(1.f + __builtin_amdgcn_exp2f(-1.4426950408889634f * x)); }
;   DI void operator()(const f32x4 (&acc)[2][2][4][2], const pg8::Unit& u, int wr, int wc, int fr, int fq) const {
;     ...
;             const f32x4 v0 = acc[ai][bj][m][0], v1 = acc[ai][bj][m][1];
;             const uint4 g = gs[m][bj];
;             f32x4 q0 = {lo2f(g.x) * v0[0], hi2f(g.x) * v0[1], lo2f(g.y) * v0[2], hi2f(g.y) * v0[3]};
;             f32x4 q1 = {lo2f(g.z) * v1[0], hi2f(g.z) * v1[1], lo2f(g.w) * v1[2], hi2f(g.w) * v1[3]};
;             st8(o0 + (size_t)(row0 + ai * 128 + m * 16) * DFF + col0 + bj * 128, q0, q1);
; DI void conv_phase(const Params& p, int l) {
;     ...
;     rows[0] = (s0 > 0) ? *(const uint4*)(gp - DFF) : z;
; #pragma unroll
;     for (int i = 0; i < RUN; ++i) rows[i + 1] = *(const uint4*)(gp + (size_t)i * DFF);
;     rows[RUN + 1] = (s0 + RUN - 1 < S - 1) ? *(const uint4*)(gp + (size_t)RUN * DFF) : z;
;     float w0[8], w1[8], w2[8], bb[8];
;     load8f(cw + c0, w0); load8f(cw + DFF + c0, w1); load8f(cw + 2 * DFF + c0, w2); load8f(cb + c0, bb);
;     float prev[8], cur[8], nxt[8];
;     unpack8(rows[0], prev); unpack8(rows[1], cur);
; #pragma unroll
;     for (int i = 0; i < RUN; ++i) {
;       unpack8(rows[i + 2], nxt);
;       float o[8];
; #pragma unroll
;       for (int j = 0; j < 8; ++j) { const float g = w0[j] * prev[j] + w1[j] * cur[j] + w2[j] * nxt[j] + bb[j]; o[j] = g * sigmoidf_(g); }
;       uint4 oo; oo.x = pack2(o[0], o[1]); oo.y = pack2(o[2], o[3]); oo.z = pack2(o[4], o[5]); oo.w = pack2(o[6], o[7]);
;       *(uint4*)(GS + (size_t)(t0 + i) * DFF + c0) = oo;
	v_lshlrev_b32_e32 v240, 16, v198
	v_and_b32_e32 v241, 0xffff0000, v198
	v_lshlrev_b32_e32 v242, 16, v202
	v_and_b32_e32 v243, 0xffff0000, v202
	v_lshlrev_b32_e32 v252, 16, v206
	v_and_b32_e32 v253, 0xffff0000, v206
	v_fma_f32 v254, v130, v240, v154
	v_fma_f32 v255, v131, v241, v155
	v_fma_f32 v254, v138, v242, v254
	v_fma_f32 v255, v139, v243, v255
	v_fma_f32 v254, v146, v252, v254
	v_fma_f32 v255, v147, v253, v255
	v_mul_f32_e32 v240, 0xbfb8aa3b, v254
	v_mul_f32_e32 v241, 0xbfb8aa3b, v255
	v_exp_f32_e32 v240, v240
	v_exp_f32_e32 v241, v241
	v_add_f32_e32 v240, 1.0, v240
	v_add_f32_e32 v241, 1.0, v241
	v_rcp_f32_e32 v240, v240
	v_rcp_f32_e32 v241, v241
	v_mul_f32_e32 v254, v254, v240
	v_mul_f32_e32 v255, v255, v241
	v_mul_f32_e32 v254, v254, v86
	v_mul_f32_e32 v255, v255, v87
	v_cvt_pk_bf16_f32 v248, v254, v255
	v_lshlrev_b32_e32 v240, 16, v199
	v_and_b32_e32 v241, 0xffff0000, v199
	v_lshlrev_b32_e32 v242, 16, v203
	v_and_b32_e32 v243, 0xffff0000, v203
	v_lshlrev_b32_e32 v252, 16, v207
	v_and_b32_e32 v253, 0xffff0000, v207
	v_fma_f32 v254, v132, v240, v156
	v_fma_f32 v255, v133, v241, v157
	v_fma_f32 v254, v140, v242, v254
	v_fma_f32 v255, v141, v243, v255
	v_fma_f32 v254, v148, v252, v254
	v_fma_f32 v255, v149, v253, v255
	v_mul_f32_e32 v240, 0xbfb8aa3b, v254
	v_mul_f32_e32 v241, 0xbfb8aa3b, v255
	v_exp_f32_e32 v240, v240
	v_exp_f32_e32 v241, v241
	v_add_f32_e32 v240, 1.0, v240
	v_add_f32_e32 v241, 1.0, v241
	v_rcp_f32_e32 v240, v240
	v_rcp_f32_e32 v241, v241
	v_mul_f32_e32 v254, v254, v240
	v_mul_f32_e32 v255, v255, v241
	v_mul_f32_e32 v254, v254, v88
	v_mul_f32_e32 v255, v255, v89
	v_cvt_pk_bf16_f32 v249, v254, v255
	v_lshlrev_b32_e32 v240, 16, v200
	v_and_b32_e32 v241, 0xffff0000, v200
	v_lshlrev_b32_e32 v242, 16, v204
	v_and_b32_e32 v243, 0xffff0000, v204
	v_lshlrev_b32_e32 v252, 16, v208
	v_and_b32_e32 v253, 0xffff0000, v208
	v_fma_f32 v254, v134, v240, v158
	v_fma_f32 v255, v135, v241, v159
	v_fma_f32 v254, v142, v242, v254
	v_fma_f32 v255, v143, v243, v255
	v_fma_f32 v254, v150, v252, v254
	v_fma_f32 v255, v151, v253, v255
	v_mul_f32_e32 v240, 0xbfb8aa3b, v254
	v_mul_f32_e32 v241, 0xbfb8aa3b, v255
	v_exp_f32_e32 v240, v240
	v_exp_f32_e32 v241, v241
	v_add_f32_e32 v240, 1.0, v240
	v_add_f32_e32 v241, 1.0, v241
	v_rcp_f32_e32 v240, v240
	v_rcp_f32_e32 v241, v241
	v_mul_f32_e32 v254, v254, v240
	v_mul_f32_e32 v255, v255, v241
	v_mul_f32_e32 v254, v254, v82
	v_mul_f32_e32 v255, v255, v83
	v_cvt_pk_bf16_f32 v250, v254, v255
	v_lshlrev_b32_e32 v240, 16, v201
	v_and_b32_e32 v241, 0xffff0000, v201
	v_lshlrev_b32_e32 v242, 16, v205
	v_and_b32_e32 v243, 0xffff0000, v205
	v_lshlrev_b32_e32 v252, 16, v209
	v_and_b32_e32 v253, 0xffff0000, v209
	v_fma_f32 v254, v136, v240, v160
	v_fma_f32 v255, v137, v241, v161
	v_fma_f32 v254, v144, v242, v254
	v_fma_f32 v255, v145, v243, v255
	v_fma_f32 v254, v152, v252, v254
	v_fma_f32 v255, v153, v253, v255
	v_mul_f32_e32 v240, 0xbfb8aa3b, v254
	v_mul_f32_e32 v241, 0xbfb8aa3b, v255
	v_exp_f32_e32 v240, v240
	v_exp_f32_e32 v241, v241
	v_add_f32_e32 v240, 1.0, v240
	v_add_f32_e32 v241, 1.0, v241
	v_rcp_f32_e32 v240, v240
	v_rcp_f32_e32 v241, v241
	v_mul_f32_e32 v254, v254, v240
	v_mul_f32_e32 v255, v255, v241
	v_mul_f32_e32 v254, v254, v84
	v_mul_f32_e32 v255, v255, v85
	v_cvt_pk_bf16_f32 v251, v254, v255
	global_store_dwordx4 v[220:221], v[248:251], off
	v_add_u32_e32 v183, 0x8f, v176
	v_mad_i64_i32 v[222:223], s[0:1], v183, s14, v[180:181]
	v_lshl_add_u64 v[224:225], v[222:223], 0, s[98:99]
	v_lshl_add_u64 v[226:227], v[224:225], 0, s[98:99]
	v_lshl_add_u64 v[220:221], v[224:225], 0, s[100:101]
	global_load_dwordx4 v[198:201], v[222:223], off
	global_load_dwordx4 v[202:205], v[224:225], off
	global_load_dwordx4 v[206:209], v[226:227], off
	s_waitcnt vmcnt(4)
	v_lshlrev_b32_e32 v240, 16, v184
	v_and_b32_e32 v241, 0xffff0000, v184
	v_lshlrev_b32_e32 v242, 16, v188
	v_and_b32_e32 v243, 0xffff0000, v188
	v_lshlrev_b32_e32 v252, 16, v192
	v_and_b32_e32 v253, 0xffff0000, v192
	v_fma_f32 v254, v130, v240, v154
	v_fma_f32 v255, v131, v241, v155
	v_fma_f32 v254, v138, v242, v254
	v_fma_f32 v255, v139, v243, v255
	v_fma_f32 v254, v146, v252, v254
	v_fma_f32 v255, v147, v253, v255
	v_mul_f32_e32 v240, 0xbfb8aa3b, v254
	v_mul_f32_e32 v241, 0xbfb8aa3b, v255
	v_exp_f32_e32 v240, v240
	v_exp_f32_e32 v241, v241
	v_add_f32_e32 v240, 1.0, v240
	v_add_f32_e32 v241, 1.0, v241
	v_rcp_f32_e32 v240, v240
	v_rcp_f32_e32 v241, v241
	v_mul_f32_e32 v254, v254, v240
	v_mul_f32_e32 v255, v255, v241
	v_mul_f32_e32 v254, v254, v62
	v_mul_f32_e32 v255, v255, v63
	v_cvt_pk_bf16_f32 v244, v254, v255
	v_lshlrev_b32_e32 v240, 16, v185
	v_and_b32_e32 v241, 0xffff0000, v185
	v_lshlrev_b32_e32 v242, 16, v189
	v_and_b32_e32 v243, 0xffff0000, v189
	v_lshlrev_b32_e32 v252, 16, v193
	v_and_b32_e32 v253, 0xffff0000, v193
	v_fma_f32 v254, v132, v240, v156
	v_fma_f32 v255, v133, v241, v157
	v_fma_f32 v254, v140, v242, v254
	v_fma_f32 v255, v141, v243, v255
	v_fma_f32 v254, v148, v252, v254
	v_fma_f32 v255, v149, v253, v255
	v_mul_f32_e32 v240, 0xbfb8aa3b, v254
	v_mul_f32_e32 v241, 0xbfb8aa3b, v255
	v_exp_f32_e32 v240, v240
	v_exp_f32_e32 v241, v241
	v_add_f32_e32 v240, 1.0, v240
	v_add_f32_e32 v241, 1.0, v241
	v_rcp_f32_e32 v240, v240
	v_rcp_f32_e32 v241, v241
	v_mul_f32_e32 v254, v254, v240
	v_mul_f32_e32 v255, v255, v241
	v_mul_f32_e32 v254, v254, v64
	v_mul_f32_e32 v255, v255, v65
	v_cvt_pk_bf16_f32 v245, v254, v255
	v_lshlrev_b32_e32 v240, 16, v186
	v_and_b32_e32 v241, 0xffff0000, v186
	v_lshlrev_b32_e32 v242, 16, v190
	v_and_b32_e32 v243, 0xffff0000, v190
	v_lshlrev_b32_e32 v252, 16, v194
	v_and_b32_e32 v253, 0xffff0000, v194
; DI unsigned pack2(float a, float b) { f32x2_t v = {a, b}; bf16x2_t r = __builtin_convertvector(v, bf16x2_t); return __builtin_bit_cast(unsigned, r); }
; DI float lo2f(unsigned u) { return __uint_as_float(u << 16); }
; DI float hi2f(unsigned u) { return __uint_as_float(u & 0xffff0000u); }
; DI float sigmoidf_(float x) { return __builtin_amdgcn_rcpf(1.f + __builtin_amdgcn_exp2f(-1.4426950408889634f * x)); }
;   DI void operator()(const f32x4 (&acc)[2][2][4][2], const pg8::Unit& u, int wr, int wc, int fr, int fq) const {
;     ...
;             const f32x4 v0 = acc[ai][bj][m][0], v1 = acc[ai][bj][m][1];
;             const uint4 g = gs[m][bj];
;             f32x4 q0 = {lo2f(g.x) * v0[0], hi2f(g.x) * v0[1], lo2f(g.y) * v0[2], hi2f(g.y) * v0[3]};
;             f32x4 q1 = {lo2f(g.z) * v1[0], hi2f(g.z) * v1[1], lo2f(g.w) * v1[2], hi2f(g.w) * v1[3]};
;             st8(o0 + (size_t)(row0 + ai * 128 + m * 16) * DFF + col0 + bj * 128, q0, q1);
; DI void conv_phase(const Params& p, int l) {
;     ...
;     rows[0] = (s0 > 0) ? *(const uint4*)(gp - DFF) : z;
; #pragma unroll
;     for (int i = 0; i < RUN; ++i) rows[i + 1] = *(const uint4*)(gp + (size_t)i * DFF);
;     rows[RUN + 1] = (s0 + RUN - 1 < S - 1) ? *(const uint4*)(gp + (size_t)RUN * DFF) : z;
;     float w0[8], w1[8], w2[8], bb[8];
;     load8f(cw + c0, w0); load8f(cw + DFF + c0, w1); load8f(cw + 2 * DFF + c0, w2); load8f(cb + c0, bb);
;     float prev[8], cur[8], nxt[8];
;     unpack8(rows[0], prev); unpack8(rows[1], cur);
; #pragma unroll
;     for (int i = 0; i < RUN; ++i) {
;       unpack8(rows[i + 2], nxt);
;       float o[8];
; #pragma unroll
;       for (int j = 0; j < 8; ++j) { const float g = w0[j] * prev[j] + w1[j] * cur[j] + w2[j] * nxt[j] + bb[j]; o[j] = g * sigmoidf_(g); }
;       uint4 oo; oo.x = pack2(o[0], o[1]); oo.y = pack2(o[2], o[3]); oo.z = pack2(o[4], o[5]); oo.w = pack2(o[6], o[7]);
;       *(uint4*)(GS + (size_t)(t0 + i) * DFF + c0) = oo;
	v_fma_f32 v254, v134, v240, v158
	v_fma_f32 v255, v135, v241, v159
	v_fma_f32 v254, v142, v242, v254
	v_fma_f32 v255, v143, v243, v255
	v_fma_f32 v254, v150, v252, v254
	v_fma_f32 v255, v151, v253, v255
	v_mul_f32_e32 v240, 0xbfb8aa3b, v254
	v_mul_f32_e32 v241, 0xbfb8aa3b, v255
	v_exp_f32_e32 v240, v240
	v_exp_f32_e32 v241, v241
	v_add_f32_e32 v240, 1.0, v240
	v_add_f32_e32 v241, 1.0, v241
	v_rcp_f32_e32 v240, v240
	v_rcp_f32_e32 v241, v241
	v_mul_f32_e32 v254, v254, v240
	v_mul_f32_e32 v255, v255, v241
	v_mul_f32_e32 v254, v254, v58
	v_mul_f32_e32 v255, v255, v59
	v_cvt_pk_bf16_f32 v246, v254, v255
	v_lshlrev_b32_e32 v240, 16, v187
	v_and_b32_e32 v241, 0xffff0000, v187
	v_lshlrev_b32_e32 v242, 16, v191
	v_and_b32_e32 v243, 0xffff0000, v191
	v_lshlrev_b32_e32 v252, 16, v195
	v_and_b32_e32 v253, 0xffff0000, v195
	v_fma_f32 v254, v136, v240, v160
	v_fma_f32 v255, v137, v241, v161
	v_fma_f32 v254, v144, v242, v254
	v_fma_f32 v255, v145, v243, v255
	v_fma_f32 v254, v152, v252, v254
	v_fma_f32 v255, v153, v253, v255
	v_mul_f32_e32 v240, 0xbfb8aa3b, v254
	v_mul_f32_e32 v241, 0xbfb8aa3b, v255
	v_exp_f32_e32 v240, v240
	v_exp_f32_e32 v241, v241
	v_add_f32_e32 v240, 1.0, v240
	v_add_f32_e32 v241, 1.0, v241
	v_rcp_f32_e32 v240, v240
	v_rcp_f32_e32 v241, v241
	v_mul_f32_e32 v254, v254, v240
	v_mul_f32_e32 v255, v255, v241
	v_mul_f32_e32 v254, v254, v60
	v_mul_f32_e32 v255, v255, v61
	v_cvt_pk_bf16_f32 v247, v254, v255
	global_store_dwordx4 v[196:197], v[244:247], off
	v_add_u32_e32 v183, 0x9f, v176
	v_mad_i64_i32 v[222:223], s[0:1], v183, s14, v[180:181]
	v_lshl_add_u64 v[224:225], v[222:223], 0, s[98:99]
	v_lshl_add_u64 v[226:227], v[224:225], 0, s[98:99]
	v_lshl_add_u64 v[196:197], v[224:225], 0, s[100:101]
	global_load_dwordx4 v[184:187], v[222:223], off
	global_load_dwordx4 v[188:191], v[224:225], off
	global_load_dwordx4 v[192:195], v[226:227], off
	s_waitcnt vmcnt(4)
	v_lshlrev_b32_e32 v240, 16, v198
	v_and_b32_e32 v241, 0xffff0000, v198
	v_lshlrev_b32_e32 v242, 16, v202
	v_and_b32_e32 v243, 0xffff0000, v202
	v_lshlrev_b32_e32 v252, 16, v206
	v_and_b32_e32 v253, 0xffff0000, v206
	v_fma_f32 v254, v130, v240, v154
	v_fma_f32 v255, v131, v241, v155
	v_fma_f32 v254, v138, v242, v254
	v_fma_f32 v255, v139, v243, v255
	v_fma_f32 v254, v146, v252, v254
	v_fma_f32 v255, v147, v253, v255
	v_mul_f32_e32 v240, 0xbfb8aa3b, v254
	v_mul_f32_e32 v241, 0xbfb8aa3b, v255
	v_exp_f32_e32 v240, v240
	v_exp_f32_e32 v241, v241
	v_add_f32_e32 v240, 1.0, v240
	v_add_f32_e32 v241, 1.0, v241
	v_rcp_f32_e32 v240, v240
	v_rcp_f32_e32 v241, v241
	v_mul_f32_e32 v254, v254, v240
	v_mul_f32_e32 v255, v255, v241
	v_mul_f32_e32 v254, v254, v54
	v_mul_f32_e32 v255, v255, v55
	v_cvt_pk_bf16_f32 v248, v254, v255
	v_lshlrev_b32_e32 v240, 16, v199
	v_and_b32_e32 v241, 0xffff0000, v199
	v_lshlrev_b32_e32 v242, 16, v203
	v_and_b32_e32 v243, 0xffff0000, v203
	v_lshlrev_b32_e32 v252, 16, v207
	v_and_b32_e32 v253, 0xffff0000, v207
	v_fma_f32 v254, v132, v240, v156
	v_fma_f32 v255, v133, v241, v157
	v_fma_f32 v254, v140, v242, v254
	v_fma_f32 v255, v141, v243, v255
	v_fma_f32 v254, v148, v252, v254
	v_fma_f32 v255, v149, v253, v255
	v_mul_f32_e32 v240, 0xbfb8aa3b, v254
	v_mul_f32_e32 v241, 0xbfb8aa3b, v255
	v_exp_f32_e32 v240, v240
	v_exp_f32_e32 v241, v241
	v_add_f32_e32 v240, 1.0, v240
	v_add_f32_e32 v241, 1.0, v241
	v_rcp_f32_e32 v240, v240
	v_rcp_f32_e32 v241, v241
	v_mul_f32_e32 v254, v254, v240
	v_mul_f32_e32 v255, v255, v241
	v_mul_f32_e32 v254, v254, v56
	v_mul_f32_e32 v255, v255, v57
	v_cvt_pk_bf16_f32 v249, v254, v255
	v_lshlrev_b32_e32 v240, 16, v200
	v_and_b32_e32 v241, 0xffff0000, v200
	v_lshlrev_b32_e32 v242, 16, v204
	v_and_b32_e32 v243, 0xffff0000, v204
	v_lshlrev_b32_e32 v252, 16, v208
	v_and_b32_e32 v253, 0xffff0000, v208
	v_fma_f32 v254, v134, v240, v158
	v_fma_f32 v255, v135, v241, v159
	v_fma_f32 v254, v142, v242, v254
	v_fma_f32 v255, v143, v243, v255
	v_fma_f32 v254, v150, v252, v254
	v_fma_f32 v255, v151, v253, v255
	v_mul_f32_e32 v240, 0xbfb8aa3b, v254
	v_mul_f32_e32 v241, 0xbfb8aa3b, v255
	v_exp_f32_e32 v240, v240
	v_exp_f32_e32 v241, v241
	v_add_f32_e32 v240, 1.0, v240
	v_add_f32_e32 v241, 1.0, v241
	v_rcp_f32_e32 v240, v240
	v_rcp_f32_e32 v241, v241
	v_mul_f32_e32 v254, v254, v240
	v_mul_f32_e32 v255, v255, v241
	v_mul_f32_e32 v254, v254, v50
	v_mul_f32_e32 v255, v255, v51
	v_cvt_pk_bf16_f32 v250, v254, v255
	v_lshlrev_b32_e32 v240, 16, v201
	v_and_b32_e32 v241, 0xffff0000, v201
	v_lshlrev_b32_e32 v242, 16, v205
	v_and_b32_e32 v243, 0xffff0000, v205
	v_lshlrev_b32_e32 v252, 16, v209
	v_and_b32_e32 v253, 0xffff0000, v209
	v_fma_f32 v254, v136, v240, v160
	v_fma_f32 v255, v137, v241, v161
	v_fma_f32 v254, v144, v242, v254
	v_fma_f32 v255, v145, v243, v255
	v_fma_f32 v254, v152, v252, v254
	v_fma_f32 v255, v153, v253, v255
	v_mul_f32_e32 v240, 0xbfb8aa3b, v254
	v_mul_f32_e32 v241, 0xbfb8aa3b, v255
	v_exp_f32_e32 v240, v240
	v_exp_f32_e32 v241, v241
	v_add_f32_e32 v240, 1.0, v240
	v_add_f32_e32 v241, 1.0, v241
	v_rcp_f32_e32 v240, v240
	v_rcp_f32_e32 v241, v241
	v_mul_f32_e32 v254, v254, v240
	v_mul_f32_e32 v255, v255, v241
	v_mul_f32_e32 v254, v254, v52
	v_mul_f32_e32 v255, v255, v53
	v_cvt_pk_bf16_f32 v251, v254, v255
	global_store_dwordx4 v[220:221], v[248:251], off
	v_add_u32_e32 v183, 0xaf, v176
	v_mad_i64_i32 v[222:223], s[0:1], v183, s14, v[180:181]
	v_lshl_add_u64 v[224:225], v[222:223], 0, s[98:99]
	v_lshl_add_u64 v[226:227], v[224:225], 0, s[98:99]
	v_lshl_add_u64 v[220:221], v[224:225], 0, s[100:101]
	global_load_dwordx4 v[198:201], v[222:223], off
	global_load_dwordx4 v[202:205], v[224:225], off
	global_load_dwordx4 v[206:209], v[226:227], off
	s_waitcnt vmcnt(4)
; DI unsigned pack2(float a, float b) { f32x2_t v = {a, b}; bf16x2_t r = __builtin_convertvector(v, bf16x2_t); return __builtin_bit_cast(unsigned, r); }
; DI float lo2f(unsigned u) { return __uint_as_float(u << 16); }
; DI float hi2f(unsigned u) { return __uint_as_float(u & 0xffff0000u); }
; DI float sigmoidf_(float x) { return __builtin_amdgcn_rcpf(1.f + __builtin_amdgcn_exp2f(-1.4426950408889634f * x)); }
;   DI void operator()(const f32x4 (&acc)[2][2][4][2], const pg8::Unit& u, int wr, int wc, int fr, int fq) const {
;     ...
;             const f32x4 v0 = acc[ai][bj][m][0], v1 = acc[ai][bj][m][1];
;             const uint4 g = gs[m][bj];
;             f32x4 q0 = {lo2f(g.x) * v0[0], hi2f(g.x) * v0[1], lo2f(g.y) * v0[2], hi2f(g.y) * v0[3]};
;             f32x4 q1 = {lo2f(g.z) * v1[0], hi2f(g.z) * v1[1], lo2f(g.w) * v1[2], hi2f(g.w) * v1[3]};
;             st8(o0 + (size_t)(row0 + ai * 128 + m * 16) * DFF + col0 + bj * 128, q0, q1);
; DI void conv_phase(const Params& p, int l) {
;     ...
;     rows[0] = (s0 > 0) ? *(const uint4*)(gp - DFF) : z;
; #pragma unroll
;     for (int i = 0; i < RUN; ++i) rows[i + 1] = *(const uint4*)(gp + (size_t)i * DFF);
;     rows[RUN + 1] = (s0 + RUN - 1 < S - 1) ? *(const uint4*)(gp + (size_t)RUN * DFF) : z;
;     float w0[8], w1[8], w2[8], bb[8];
;     load8f(cw + c0, w0); load8f(cw + DFF + c0, w1); load8f(cw + 2 * DFF + c0, w2); load8f(cb + c0, bb);
;     float prev[8], cur[8], nxt[8];
;     unpack8(rows[0], prev); unpack8(rows[1], cur);
; #pragma unroll
;     for (int i = 0; i < RUN; ++i) {
;       unpack8(rows[i + 2], nxt);
;       float o[8];
; #pragma unroll
;       for (int j = 0; j < 8; ++j) { const float g = w0[j] * prev[j] + w1[j] * cur[j] + w2[j] * nxt[j] + bb[j]; o[j] = g * sigmoidf_(g); }
;       uint4 oo; oo.x = pack2(o[0], o[1]); oo.y = pack2(o[2], o[3]); oo.z = pack2(o[4], o[5]); oo.w = pack2(o[6], o[7]);
;       *(uint4*)(GS + (size_t)(t0 + i) * DFF + c0) = oo;
	v_lshlrev_b32_e32 v240, 16, v184
	v_and_b32_e32 v241, 0xffff0000, v184
	v_lshlrev_b32_e32 v242, 16, v188
	v_and_b32_e32 v243, 0xffff0000, v188
	v_lshlrev_b32_e32 v252, 16, v192
	v_and_b32_e32 v253, 0xffff0000, v192
	v_fma_f32 v254, v130, v240, v154
	v_fma_f32 v255, v131, v241, v155
	v_fma_f32 v254, v138, v242, v254
	v_fma_f32 v255, v139, v243, v255
	v_fma_f32 v254, v146, v252, v254
	v_fma_f32 v255, v147, v253, v255
	v_mul_f32_e32 v240, 0xbfb8aa3b, v254
	v_mul_f32_e32 v241, 0xbfb8aa3b, v255
	v_exp_f32_e32 v240, v240
	v_exp_f32_e32 v241, v241
	v_add_f32_e32 v240, 1.0, v240
	v_add_f32_e32 v241, 1.0, v241
	v_rcp_f32_e32 v240, v240
	v_rcp_f32_e32 v241, v241
	v_mul_f32_e32 v254, v254, v240
	v_mul_f32_e32 v255, v255, v241
	v_mul_f32_e32 v254, v254, v38
	v_mul_f32_e32 v255, v255, v39
	v_cvt_pk_bf16_f32 v244, v254, v255
	v_lshlrev_b32_e32 v240, 16, v185
	v_and_b32_e32 v241, 0xffff0000, v185
	v_lshlrev_b32_e32 v242, 16, v189
	v_and_b32_e32 v243, 0xffff0000, v189
	v_lshlrev_b32_e32 v252, 16, v193
	v_and_b32_e32 v253, 0xffff0000, v193
	v_fma_f32 v254, v132, v240, v156
	v_fma_f32 v255, v133, v241, v157
	v_fma_f32 v254, v140, v242, v254
	v_fma_f32 v255, v141, v243, v255
	v_fma_f32 v254, v148, v252, v254
	v_fma_f32 v255, v149, v253, v255
	v_mul_f32_e32 v240, 0xbfb8aa3b, v254
	v_mul_f32_e32 v241, 0xbfb8aa3b, v255
	v_exp_f32_e32 v240, v240
	v_exp_f32_e32 v241, v241
	v_add_f32_e32 v240, 1.0, v240
	v_add_f32_e32 v241, 1.0, v241
	v_rcp_f32_e32 v240, v240
	v_rcp_f32_e32 v241, v241
	v_mul_f32_e32 v254, v254, v240
	v_mul_f32_e32 v255, v255, v241
	v_mul_f32_e32 v254, v254, v40
	v_mul_f32_e32 v255, v255, v41
	v_cvt_pk_bf16_f32 v245, v254, v255
	v_lshlrev_b32_e32 v240, 16, v186
	v_and_b32_e32 v241, 0xffff0000, v186
	v_lshlrev_b32_e32 v242, 16, v190
	v_and_b32_e32 v243, 0xffff0000, v190
	v_lshlrev_b32_e32 v252, 16, v194
	v_and_b32_e32 v253, 0xffff0000, v194
	v_fma_f32 v254, v134, v240, v158
	v_fma_f32 v255, v135, v241, v159
	v_fma_f32 v254, v142, v242, v254
	v_fma_f32 v255, v143, v243, v255
	v_fma_f32 v254, v150, v252, v254
	v_fma_f32 v255, v151, v253, v255
	v_mul_f32_e32 v240, 0xbfb8aa3b, v254
	v_mul_f32_e32 v241, 0xbfb8aa3b, v255
	v_exp_f32_e32 v240, v240
	v_exp_f32_e32 v241, v241
	v_add_f32_e32 v240, 1.0, v240
	v_add_f32_e32 v241, 1.0, v241
	v_rcp_f32_e32 v240, v240
	v_rcp_f32_e32 v241, v241
	v_mul_f32_e32 v254, v254, v240
	v_mul_f32_e32 v255, v255, v241
	v_mul_f32_e32 v254, v254, v34
	v_mul_f32_e32 v255, v255, v35
	v_cvt_pk_bf16_f32 v246, v254, v255
	v_lshlrev_b32_e32 v240, 16, v187
	v_and_b32_e32 v241, 0xffff0000, v187
	v_lshlrev_b32_e32 v242, 16, v191
	v_and_b32_e32 v243, 0xffff0000, v191
	v_lshlrev_b32_e32 v252, 16, v195
	v_and_b32_e32 v253, 0xffff0000, v195
	v_fma_f32 v254, v136, v240, v160
	v_fma_f32 v255, v137, v241, v161
	v_fma_f32 v254, v144, v242, v254
	v_fma_f32 v255, v145, v243, v255
	v_fma_f32 v254, v152, v252, v254
	v_fma_f32 v255, v153, v253, v255
	v_mul_f32_e32 v240, 0xbfb8aa3b, v254
	v_mul_f32_e32 v241, 0xbfb8aa3b, v255
	v_exp_f32_e32 v240, v240
	v_exp_f32_e32 v241, v241
	v_add_f32_e32 v240, 1.0, v240
	v_add_f32_e32 v241, 1.0, v241
	v_rcp_f32_e32 v240, v240
	v_rcp_f32_e32 v241, v241
	v_mul_f32_e32 v254, v254, v240
	v_mul_f32_e32 v255, v255, v241
	v_mul_f32_e32 v254, v254, v36
	v_mul_f32_e32 v255, v255, v37
	v_cvt_pk_bf16_f32 v247, v254, v255
	global_store_dwordx4 v[196:197], v[244:247], off
	s_waitcnt vmcnt(1)
	v_add_u32_e32 v183, 0xb0, v176
	v_and_b32_e32 v183, 0x1fff, v183
	v_cmp_eq_u32_e32 vcc, 0x1fff, v183
	v_cndmask_b32_e64 v206, v206, 0, vcc
	v_cndmask_b32_e64 v207, v207, 0, vcc
	v_cndmask_b32_e64 v208, v208, 0, vcc
	v_cndmask_b32_e64 v209, v209, 0, vcc
	v_lshlrev_b32_e32 v240, 16, v198
	v_and_b32_e32 v241, 0xffff0000, v198
	v_lshlrev_b32_e32 v242, 16, v202
	v_and_b32_e32 v243, 0xffff0000, v202
	v_lshlrev_b32_e32 v252, 16, v206
	v_and_b32_e32 v253, 0xffff0000, v206
	v_fma_f32 v254, v130, v240, v154
	v_fma_f32 v255, v131, v241, v155
	v_fma_f32 v254, v138, v242, v254
	v_fma_f32 v255, v139, v243, v255
	v_fma_f32 v254, v146, v252, v254
	v_fma_f32 v255, v147, v253, v255
	v_mul_f32_e32 v240, 0xbfb8aa3b, v254
	v_mul_f32_e32 v241, 0xbfb8aa3b, v255
	v_exp_f32_e32 v240, v240
	v_exp_f32_e32 v241, v241
	v_add_f32_e32 v240, 1.0, v240
	v_add_f32_e32 v241, 1.0, v241
	v_rcp_f32_e32 v240, v240
	v_rcp_f32_e32 v241, v241
	v_mul_f32_e32 v254, v254, v240
	v_mul_f32_e32 v255, v255, v241
	v_mul_f32_e32 v254, v254, v22
	v_mul_f32_e32 v255, v255, v23
	v_cvt_pk_bf16_f32 v248, v254, v255
	v_lshlrev_b32_e32 v240, 16, v199
	v_and_b32_e32 v241, 0xffff0000, v199
	v_lshlrev_b32_e32 v242, 16, v203
	v_and_b32_e32 v243, 0xffff0000, v203
	v_lshlrev_b32_e32 v252, 16, v207
	v_and_b32_e32 v253, 0xffff0000, v207
	v_fma_f32 v254, v132, v240, v156
	v_fma_f32 v255, v133, v241, v157
	v_fma_f32 v254, v140, v242, v254
	v_fma_f32 v255, v141, v243, v255
	v_fma_f32 v254, v148, v252, v254
	v_fma_f32 v255, v149, v253, v255
	v_mul_f32_e32 v240, 0xbfb8aa3b, v254
	v_mul_f32_e32 v241, 0xbfb8aa3b, v255
	v_exp_f32_e32 v240, v240
	v_exp_f32_e32 v241, v241
	v_add_f32_e32 v240, 1.0, v240
	v_add_f32_e32 v241, 1.0, v241
	v_rcp_f32_e32 v240, v240
	v_rcp_f32_e32 v241, v241
	v_mul_f32_e32 v254, v254, v240
	v_mul_f32_e32 v255, v255, v241
	v_mul_f32_e32 v254, v254, v24
	v_mul_f32_e32 v255, v255, v25
	v_cvt_pk_bf16_f32 v249, v254, v255
	v_lshlrev_b32_e32 v240, 16, v200
	v_and_b32_e32 v241, 0xffff0000, v200
	v_lshlrev_b32_e32 v242, 16, v204
	v_and_b32_e32 v243, 0xffff0000, v204
	v_lshlrev_b32_e32 v252, 16, v208
	v_and_b32_e32 v253, 0xffff0000, v208
	v_fma_f32 v254, v134, v240, v158
	v_fma_f32 v255, v135, v241, v159
	v_fma_f32 v254, v142, v242, v254
	v_fma_f32 v255, v143, v243, v255
	v_fma_f32 v254, v150, v252, v254
; DI unsigned pack2(float a, float b) { f32x2_t v = {a, b}; bf16x2_t r = __builtin_convertvector(v, bf16x2_t); return __builtin_bit_cast(unsigned, r); }
; DI float lo2f(unsigned u) { return __uint_as_float(u << 16); }
; DI float hi2f(unsigned u) { return __uint_as_float(u & 0xffff0000u); }
; DI float sigmoidf_(float x) { return __builtin_amdgcn_rcpf(1.f + __builtin_amdgcn_exp2f(-1.4426950408889634f * x)); }
;   DI void operator()(const f32x4 (&acc)[2][2][4][2], const pg8::Unit& u, int wr, int wc, int fr, int fq) const {
;     ...
;             const f32x4 v0 = acc[ai][bj][m][0], v1 = acc[ai][bj][m][1];
;             const uint4 g = gs[m][bj];
;             f32x4 q0 = {lo2f(g.x) * v0[0], hi2f(g.x) * v0[1], lo2f(g.y) * v0[2], hi2f(g.y) * v0[3]};
;             f32x4 q1 = {lo2f(g.z) * v1[0], hi2f(g.z) * v1[1], lo2f(g.w) * v1[2], hi2f(g.w) * v1[3]};
;             st8(o0 + (size_t)(row0 + ai * 128 + m * 16) * DFF + col0 + bj * 128, q0, q1);
; DI void conv_phase(const Params& p, int l) {
;     ...
;     rows[0] = (s0 > 0) ? *(const uint4*)(gp - DFF) : z;
; #pragma unroll
;     for (int i = 0; i < RUN; ++i) rows[i + 1] = *(const uint4*)(gp + (size_t)i * DFF);
;     rows[RUN + 1] = (s0 + RUN - 1 < S - 1) ? *(const uint4*)(gp + (size_t)RUN * DFF) : z;
;     float w0[8], w1[8], w2[8], bb[8];
;     load8f(cw + c0, w0); load8f(cw + DFF + c0, w1); load8f(cw + 2 * DFF + c0, w2); load8f(cb + c0, bb);
;     float prev[8], cur[8], nxt[8];
;     unpack8(rows[0], prev); unpack8(rows[1], cur);
; #pragma unroll
;     for (int i = 0; i < RUN; ++i) {
;       unpack8(rows[i + 2], nxt);
;       float o[8];
; #pragma unroll
;       for (int j = 0; j < 8; ++j) { const float g = w0[j] * prev[j] + w1[j] * cur[j] + w2[j] * nxt[j] + bb[j]; o[j] = g * sigmoidf_(g); }
;       uint4 oo; oo.x = pack2(o[0], o[1]); oo.y = pack2(o[2], o[3]); oo.z = pack2(o[4], o[5]); oo.w = pack2(o[6], o[7]);
;       *(uint4*)(GS + (size_t)(t0 + i) * DFF + c0) = oo;
	v_fma_f32 v255, v151, v253, v255
	v_mul_f32_e32 v240, 0xbfb8aa3b, v254
	v_mul_f32_e32 v241, 0xbfb8aa3b, v255
	v_exp_f32_e32 v240, v240
	v_exp_f32_e32 v241, v241
	v_add_f32_e32 v240, 1.0, v240
	v_add_f32_e32 v241, 1.0, v241
	v_rcp_f32_e32 v240, v240
	v_rcp_f32_e32 v241, v241
	v_mul_f32_e32 v254, v254, v240
	v_mul_f32_e32 v255, v255, v241
	v_mul_f32_e32 v254, v254, v18
	v_mul_f32_e32 v255, v255, v19
	v_cvt_pk_bf16_f32 v250, v254, v255
	v_lshlrev_b32_e32 v240, 16, v201
	v_and_b32_e32 v241, 0xffff0000, v201
	v_lshlrev_b32_e32 v242, 16, v205
	v_and_b32_e32 v243, 0xffff0000, v205
	v_lshlrev_b32_e32 v252, 16, v209
	v_and_b32_e32 v253, 0xffff0000, v209
	v_fma_f32 v254, v136, v240, v160
	v_fma_f32 v255, v137, v241, v161
	v_fma_f32 v254, v144, v242, v254
	v_fma_f32 v255, v145, v243, v255
	v_fma_f32 v254, v152, v252, v254
	v_fma_f32 v255, v153, v253, v255
	v_mul_f32_e32 v240, 0xbfb8aa3b, v254
	v_mul_f32_e32 v241, 0xbfb8aa3b, v255
	v_exp_f32_e32 v240, v240
	v_exp_f32_e32 v241, v241
	v_add_f32_e32 v240, 1.0, v240
	v_add_f32_e32 v241, 1.0, v241
	v_rcp_f32_e32 v240, v240
	v_rcp_f32_e32 v241, v241
	v_mul_f32_e32 v254, v254, v240
	v_mul_f32_e32 v255, v255, v241
	v_mul_f32_e32 v254, v254, v20
	v_mul_f32_e32 v255, v255, v21
	v_cvt_pk_bf16_f32 v251, v254, v255
	global_store_dwordx4 v[220:221], v[248:251], off
	v_readlane_b32 s98, v237, 62
	v_readlane_b32 s100, v238, 0
	v_readlane_b32 s101, v238, 1
	s_mul_i32 s98, s98, 0xab
	s_bfe_u32 s98, s98, 0x6000a
	s_mul_i32 s99, s98, 0x8400
	s_add_u32 s100, s100, s99
	s_addc_u32 s101, s101, 0
	s_nop 3
	global_load_dwordx4 v[130:133], v182, s[100:101] offset:512
	global_load_dwordx4 v[134:137], v182, s[100:101] offset:528
	s_add_u32 s100, s100, 0x2c00
	s_addc_u32 s101, s101, 0
	global_load_dwordx4 v[138:141], v182, s[100:101] offset:512
	global_load_dwordx4 v[142:145], v182, s[100:101] offset:528
	s_add_u32 s100, s100, 0x2c00
	s_addc_u32 s101, s101, 0
	global_load_dwordx4 v[146:149], v182, s[100:101] offset:512
	global_load_dwordx4 v[150:153], v182, s[100:101] offset:528
	v_readlane_b32 s100, v238, 2
	v_readlane_b32 s101, v238, 3
	s_mul_i32 s99, s98, 0x2c00
	s_add_u32 s100, s100, s99
	s_addc_u32 s101, s101, 0
	s_nop 3
	global_load_dwordx4 v[154:157], v182, s[100:101] offset:512
	global_load_dwordx4 v[158:161], v182, s[100:101] offset:528
	s_mov_b32 s98, 0x1600
	s_mov_b32 s99, 0
	s_mov_b32 s100, 0x16000000
	s_mov_b32 s101, 0
	v_add_u32_e32 v183, -1, v176
	v_mad_i64_i32 v[222:223], s[0:1], v183, s14, v[180:181]
	v_lshl_add_u64 v[224:225], v[222:223], 0, s[98:99]
	v_lshl_add_u64 v[226:227], v[224:225], 0, s[98:99]
	v_lshl_add_u64 v[196:197], v[224:225], 0, s[100:101]
	global_load_dwordx4 v[184:187], v[222:223], off offset:256
	global_load_dwordx4 v[188:191], v[224:225], off offset:256
	global_load_dwordx4 v[192:195], v[226:227], off offset:256
	v_add_u32_e32 v183, 0xf, v176
	v_mad_i64_i32 v[222:223], s[0:1], v183, s14, v[180:181]
	v_lshl_add_u64 v[224:225], v[222:223], 0, s[98:99]
	v_lshl_add_u64 v[226:227], v[224:225], 0, s[98:99]
	v_lshl_add_u64 v[220:221], v[224:225], 0, s[100:101]
	global_load_dwordx4 v[198:201], v[222:223], off offset:256
	global_load_dwordx4 v[202:205], v[224:225], off offset:256
	global_load_dwordx4 v[206:209], v[226:227], off offset:256
	s_waitcnt vmcnt(3)
	v_and_b32_e32 v183, 0x1fff, v176
	v_cmp_eq_u32_e32 vcc, 0, v183
	v_cndmask_b32_e64 v184, v184, 0, vcc
	v_cndmask_b32_e64 v185, v185, 0, vcc
	v_cndmask_b32_e64 v186, v186, 0, vcc
	v_cndmask_b32_e64 v187, v187, 0, vcc
	v_lshlrev_b32_e32 v240, 16, v184
	v_and_b32_e32 v241, 0xffff0000, v184
	v_lshlrev_b32_e32 v242, 16, v188
	v_and_b32_e32 v243, 0xffff0000, v188
	v_lshlrev_b32_e32 v252, 16, v192
	v_and_b32_e32 v253, 0xffff0000, v192
	v_fma_f32 v254, v130, v240, v154
	v_fma_f32 v255, v131, v241, v155
	v_fma_f32 v254, v138, v242, v254
	v_fma_f32 v255, v139, v243, v255
	v_fma_f32 v254, v146, v252, v254
	v_fma_f32 v255, v147, v253, v255
	v_mul_f32_e32 v240, 0xbfb8aa3b, v254
	v_mul_f32_e32 v241, 0xbfb8aa3b, v255
	v_exp_f32_e32 v240, v240
	v_exp_f32_e32 v241, v241
	v_add_f32_e32 v240, 1.0, v240
	v_add_f32_e32 v241, 1.0, v241
	v_rcp_f32_e32 v240, v240
	v_rcp_f32_e32 v241, v241
	v_mul_f32_e32 v254, v254, v240
	v_mul_f32_e32 v255, v255, v241
	v_mul_f32_e32 v254, v254, v110
	v_mul_f32_e32 v255, v255, v111
	v_cvt_pk_bf16_f32 v244, v254, v255
	v_lshlrev_b32_e32 v240, 16, v185
	v_and_b32_e32 v241, 0xffff0000, v185
	v_lshlrev_b32_e32 v242, 16, v189
	v_and_b32_e32 v243, 0xffff0000, v189
	v_lshlrev_b32_e32 v252, 16, v193
	v_and_b32_e32 v253, 0xffff0000, v193
	v_fma_f32 v254, v132, v240, v156
	v_fma_f32 v255, v133, v241, v157
	v_fma_f32 v254, v140, v242, v254
	v_fma_f32 v255, v141, v243, v255
	v_fma_f32 v254, v148, v252, v254
	v_fma_f32 v255, v149, v253, v255
	v_mul_f32_e32 v240, 0xbfb8aa3b, v254
	v_mul_f32_e32 v241, 0xbfb8aa3b, v255
	v_exp_f32_e32 v240, v240
	v_exp_f32_e32 v241, v241
	v_add_f32_e32 v240, 1.0, v240
	v_add_f32_e32 v241, 1.0, v241
	v_rcp_f32_e32 v240, v240
	v_rcp_f32_e32 v241, v241
	v_mul_f32_e32 v254, v254, v240
	v_mul_f32_e32 v255, v255, v241
	v_mul_f32_e32 v254, v254, v112
	v_mul_f32_e32 v255, v255, v113
	v_cvt_pk_bf16_f32 v245, v254, v255
	v_lshlrev_b32_e32 v240, 16, v186
	v_and_b32_e32 v241, 0xffff0000, v186
	v_lshlrev_b32_e32 v242, 16, v190
	v_and_b32_e32 v243, 0xffff0000, v190
	v_lshlrev_b32_e32 v252, 16, v194
	v_and_b32_e32 v253, 0xffff0000, v194
	v_fma_f32 v254, v134, v240, v158
	v_fma_f32 v255, v135, v241, v159
	v_fma_f32 v254, v142, v242, v254
	v_fma_f32 v255, v143, v243, v255
	v_fma_f32 v254, v150, v252, v254
	v_fma_f32 v255, v151, v253, v255
	v_mul_f32_e32 v240, 0xbfb8aa3b, v254
	v_mul_f32_e32 v241, 0xbfb8aa3b, v255
	v_exp_f32_e32 v240, v240
; DI unsigned pack2(float a, float b) { f32x2_t v = {a, b}; bf16x2_t r = __builtin_convertvector(v, bf16x2_t); return __builtin_bit_cast(unsigned, r); }
; DI float lo2f(unsigned u) { return __uint_as_float(u << 16); }
; DI float hi2f(unsigned u) { return __uint_as_float(u & 0xffff0000u); }
; DI float sigmoidf_(float x) { return __builtin_amdgcn_rcpf(1.f + __builtin_amdgcn_exp2f(-1.4426950408889634f * x)); }
;   DI void operator()(const f32x4 (&acc)[2][2][4][2], const pg8::Unit& u, int wr, int wc, int fr, int fq) const {
;     ...
;     } else {
; #pragma unroll
;       for (int ai = 0; ai < 2; ++ai) {
;         uint4 gs[4][2];
; #pragma unroll
;         for (int m = 0; m < 4; ++m)
; #pragma unroll
;           for (int bj = 0; bj < 2; ++bj)
;             gs[m][bj] = *(const uint4*)(o0 + (size_t)(row0 + ai * 128 + m * 16) * DFF + col0 + bj * 128);
;         __builtin_amdgcn_sched_barrier(0);
; #pragma unroll
;         for (int m = 0; m < 4; ++m)
; #pragma unroll
;           for (int bj = 0; bj < 2; ++bj) {
;             const f32x4 v0 = acc[ai][bj][m][0], v1 = acc[ai][bj][m][1];
;             const uint4 g = gs[m][bj];
;             f32x4 q0 = {lo2f(g.x) * v0[0], hi2f(g.x) * v0[1], lo2f(g.y) * v0[2], hi2f(g.y) * v0[3]};
;             f32x4 q1 = {lo2f(g.z) * v1[0], hi2f(g.z) * v1[1], lo2f(g.w) * v1[2], hi2f(g.w) * v1[3]};
;             st8(o0 + (size_t)(row0 + ai * 128 + m * 16) * DFF + col0 + bj * 128, q0, q1);
;           }
;         __builtin_amdgcn_sched_barrier(0);
;       }
; DI void conv_phase(const Params& p, int l) {
;     ...
;     for (int i = 0; i < RUN; ++i) {
;       unpack8(rows[i + 2], nxt);
;       float o[8];
; #pragma unroll
;       for (int j = 0; j < 8; ++j) { const float g = w0[j] * prev[j] + w1[j] * cur[j] + w2[j] * nxt[j] + bb[j]; o[j] = g * sigmoidf_(g); }
;       uint4 oo; oo.x = pack2(o[0], o[1]); oo.y = pack2(o[2], o[3]); oo.z = pack2(o[4], o[5]); oo.w = pack2(o[6], o[7]);
;       *(uint4*)(GS + (size_t)(t0 + i) * DFF + c0) = oo;
	v_exp_f32_e32 v241, v241
	v_add_f32_e32 v240, 1.0, v240
	v_add_f32_e32 v241, 1.0, v241
	v_rcp_f32_e32 v240, v240
	v_rcp_f32_e32 v241, v241
	v_mul_f32_e32 v254, v254, v240
	v_mul_f32_e32 v255, v255, v241
	v_mul_f32_e32 v254, v254, v106
	v_mul_f32_e32 v255, v255, v107
	v_cvt_pk_bf16_f32 v246, v254, v255
	v_lshlrev_b32_e32 v240, 16, v187
	v_and_b32_e32 v241, 0xffff0000, v187
	v_lshlrev_b32_e32 v242, 16, v191
	v_and_b32_e32 v243, 0xffff0000, v191
	v_lshlrev_b32_e32 v252, 16, v195
	v_and_b32_e32 v253, 0xffff0000, v195
	v_fma_f32 v254, v136, v240, v160
	v_fma_f32 v255, v137, v241, v161
	v_fma_f32 v254, v144, v242, v254
	v_fma_f32 v255, v145, v243, v255
	v_fma_f32 v254, v152, v252, v254
	v_fma_f32 v255, v153, v253, v255
	v_mul_f32_e32 v240, 0xbfb8aa3b, v254
	v_mul_f32_e32 v241, 0xbfb8aa3b, v255
	v_exp_f32_e32 v240, v240
	v_exp_f32_e32 v241, v241
	v_add_f32_e32 v240, 1.0, v240
	v_add_f32_e32 v241, 1.0, v241
	v_rcp_f32_e32 v240, v240
	v_rcp_f32_e32 v241, v241
	v_mul_f32_e32 v254, v254, v240
	v_mul_f32_e32 v255, v255, v241
	v_mul_f32_e32 v254, v254, v108
	v_mul_f32_e32 v255, v255, v109
	v_cvt_pk_bf16_f32 v247, v254, v255
	global_store_dwordx4 v[196:197], v[244:247], off offset:256
	v_add_u32_e32 v183, 0x1f, v176
	v_mad_i64_i32 v[222:223], s[0:1], v183, s14, v[180:181]
	v_lshl_add_u64 v[224:225], v[222:223], 0, s[98:99]
	v_lshl_add_u64 v[226:227], v[224:225], 0, s[98:99]
	v_lshl_add_u64 v[196:197], v[224:225], 0, s[100:101]
	global_load_dwordx4 v[184:187], v[222:223], off offset:256
	global_load_dwordx4 v[188:191], v[224:225], off offset:256
	global_load_dwordx4 v[192:195], v[226:227], off offset:256
	s_waitcnt vmcnt(4)
	v_lshlrev_b32_e32 v240, 16, v198
	v_and_b32_e32 v241, 0xffff0000, v198
	v_lshlrev_b32_e32 v242, 16, v202
	v_and_b32_e32 v243, 0xffff0000, v202
	v_lshlrev_b32_e32 v252, 16, v206
	v_and_b32_e32 v253, 0xffff0000, v206
	v_fma_f32 v254, v130, v240, v154
	v_fma_f32 v255, v131, v241, v155
	v_fma_f32 v254, v138, v242, v254
	v_fma_f32 v255, v139, v243, v255
	v_fma_f32 v254, v146, v252, v254
	v_fma_f32 v255, v147, v253, v255
	v_mul_f32_e32 v240, 0xbfb8aa3b, v254
	v_mul_f32_e32 v241, 0xbfb8aa3b, v255
	v_exp_f32_e32 v240, v240
	v_exp_f32_e32 v241, v241
	v_add_f32_e32 v240, 1.0, v240
	v_add_f32_e32 v241, 1.0, v241
	v_rcp_f32_e32 v240, v240
	v_rcp_f32_e32 v241, v241
	v_mul_f32_e32 v254, v254, v240
	v_mul_f32_e32 v255, v255, v241
	v_mul_f32_e32 v254, v254, v94
	v_mul_f32_e32 v255, v255, v95
	v_cvt_pk_bf16_f32 v248, v254, v255
	v_lshlrev_b32_e32 v240, 16, v199
	v_and_b32_e32 v241, 0xffff0000, v199
	v_lshlrev_b32_e32 v242, 16, v203
	v_and_b32_e32 v243, 0xffff0000, v203
	v_lshlrev_b32_e32 v252, 16, v207
	v_and_b32_e32 v253, 0xffff0000, v207
	v_fma_f32 v254, v132, v240, v156
	v_fma_f32 v255, v133, v241, v157
	v_fma_f32 v254, v140, v242, v254
	v_fma_f32 v255, v141, v243, v255
	v_fma_f32 v254, v148, v252, v254
	v_fma_f32 v255, v149, v253, v255
	v_mul_f32_e32 v240, 0xbfb8aa3b, v254
	v_mul_f32_e32 v241, 0xbfb8aa3b, v255
	v_exp_f32_e32 v240, v240
	v_exp_f32_e32 v241, v241
	v_add_f32_e32 v240, 1.0, v240
	v_add_f32_e32 v241, 1.0, v241
	v_rcp_f32_e32 v240, v240
	v_rcp_f32_e32 v241, v241
	v_mul_f32_e32 v254, v254, v240
	v_mul_f32_e32 v255, v255, v241
	v_mul_f32_e32 v254, v254, v96
	v_mul_f32_e32 v255, v255, v97
	v_cvt_pk_bf16_f32 v249, v254, v255
	v_lshlrev_b32_e32 v240, 16, v200
	v_and_b32_e32 v241, 0xffff0000, v200
	v_lshlrev_b32_e32 v242, 16, v204
	v_and_b32_e32 v243, 0xffff0000, v204
	v_lshlrev_b32_e32 v252, 16, v208
	v_and_b32_e32 v253, 0xffff0000, v208
	v_fma_f32 v254, v134, v240, v158
	v_fma_f32 v255, v135, v241, v159
	v_fma_f32 v254, v142, v242, v254
	v_fma_f32 v255, v143, v243, v255
	v_fma_f32 v254, v150, v252, v254
	v_fma_f32 v255, v151, v253, v255
	v_mul_f32_e32 v240, 0xbfb8aa3b, v254
	v_mul_f32_e32 v241, 0xbfb8aa3b, v255
	v_exp_f32_e32 v240, v240
	v_exp_f32_e32 v241, v241
	v_add_f32_e32 v240, 1.0, v240
	v_add_f32_e32 v241, 1.0, v241
	v_rcp_f32_e32 v240, v240
	v_rcp_f32_e32 v241, v241
	v_mul_f32_e32 v254, v254, v240
	v_mul_f32_e32 v255, v255, v241
	v_mul_f32_e32 v254, v254, v90
	v_mul_f32_e32 v255, v255, v91
	v_cvt_pk_bf16_f32 v250, v254, v255
	v_lshlrev_b32_e32 v240, 16, v201
	v_and_b32_e32 v241, 0xffff0000, v201
	v_lshlrev_b32_e32 v242, 16, v205
	v_and_b32_e32 v243, 0xffff0000, v205
	v_lshlrev_b32_e32 v252, 16, v209
	v_and_b32_e32 v253, 0xffff0000, v209
	v_fma_f32 v254, v136, v240, v160
	v_fma_f32 v255, v137, v241, v161
	v_fma_f32 v254, v144, v242, v254
	v_fma_f32 v255, v145, v243, v255
	v_fma_f32 v254, v152, v252, v254
	v_fma_f32 v255, v153, v253, v255
	v_mul_f32_e32 v240, 0xbfb8aa3b, v254
	v_mul_f32_e32 v241, 0xbfb8aa3b, v255
	v_exp_f32_e32 v240, v240
	v_exp_f32_e32 v241, v241
	v_add_f32_e32 v240, 1.0, v240
	v_add_f32_e32 v241, 1.0, v241
	v_rcp_f32_e32 v240, v240
	v_rcp_f32_e32 v241, v241
	v_mul_f32_e32 v254, v254, v240
	v_mul_f32_e32 v255, v255, v241
	v_mul_f32_e32 v254, v254, v92
	v_mul_f32_e32 v255, v255, v93
	v_cvt_pk_bf16_f32 v251, v254, v255
	global_store_dwordx4 v[220:221], v[248:251], off offset:256
	v_add_u32_e32 v183, 0x2f, v176
	v_mad_i64_i32 v[222:223], s[0:1], v183, s14, v[180:181]
	v_lshl_add_u64 v[224:225], v[222:223], 0, s[98:99]
	v_lshl_add_u64 v[226:227], v[224:225], 0, s[98:99]
	v_lshl_add_u64 v[220:221], v[224:225], 0, s[100:101]
	global_load_dwordx4 v[198:201], v[222:223], off offset:256
	global_load_dwordx4 v[202:205], v[224:225], off offset:256
	global_load_dwordx4 v[206:209], v[226:227], off offset:256
	s_waitcnt vmcnt(4)
; DI unsigned pack2(float a, float b) { f32x2_t v = {a, b}; bf16x2_t r = __builtin_convertvector(v, bf16x2_t); return __builtin_bit_cast(unsigned, r); }
; DI float lo2f(unsigned u) { return __uint_as_float(u << 16); }
; DI float hi2f(unsigned u) { return __uint_as_float(u & 0xffff0000u); }
; DI float sigmoidf_(float x) { return __builtin_amdgcn_rcpf(1.f + __builtin_amdgcn_exp2f(-1.4426950408889634f * x)); }
;   DI void operator()(const f32x4 (&acc)[2][2][4][2], const pg8::Unit& u, int wr, int wc, int fr, int fq) const {
;     ...
;     } else {
; #pragma unroll
;       for (int ai = 0; ai < 2; ++ai) {
;         uint4 gs[4][2];
; #pragma unroll
;         for (int m = 0; m < 4; ++m)
; #pragma unroll
;           for (int bj = 0; bj < 2; ++bj)
;             gs[m][bj] = *(const uint4*)(o0 + (size_t)(row0 + ai * 128 + m * 16) * DFF + col0 + bj * 128);
;         __builtin_amdgcn_sched_barrier(0);
; #pragma unroll
;         for (int m = 0; m < 4; ++m)
; #pragma unroll
;           for (int bj = 0; bj < 2; ++bj) {
;             const f32x4 v0 = acc[ai][bj][m][0], v1 = acc[ai][bj][m][1];
;             const uint4 g = gs[m][bj];
;             f32x4 q0 = {lo2f(g.x) * v0[0], hi2f(g.x) * v0[1], lo2f(g.y) * v0[2], hi2f(g.y) * v0[3]};
;             f32x4 q1 = {lo2f(g.z) * v1[0], hi2f(g.z) * v1[1], lo2f(g.w) * v1[2], hi2f(g.w) * v1[3]};
;             st8(o0 + (size_t)(row0 + ai * 128 + m * 16) * DFF + col0 + bj * 128, q0, q1);
;           }
;         __builtin_amdgcn_sched_barrier(0);
;       }
; DI void conv_phase(const Params& p, int l) {
;     ...
;     for (int i = 0; i < RUN; ++i) {
;       unpack8(rows[i + 2], nxt);
;       float o[8];
; #pragma unroll
;       for (int j = 0; j < 8; ++j) { const float g = w0[j] * prev[j] + w1[j] * cur[j] + w2[j] * nxt[j] + bb[j]; o[j] = g * sigmoidf_(g); }
;       uint4 oo; oo.x = pack2(o[0], o[1]); oo.y = pack2(o[2], o[3]); oo.z = pack2(o[4], o[5]); oo.w = pack2(o[6], o[7]);
;       *(uint4*)(GS + (size_t)(t0 + i) * DFF + c0) = oo;
	v_lshlrev_b32_e32 v240, 16, v184
	v_and_b32_e32 v241, 0xffff0000, v184
	v_lshlrev_b32_e32 v242, 16, v188
	v_and_b32_e32 v243, 0xffff0000, v188
	v_lshlrev_b32_e32 v252, 16, v192
	v_and_b32_e32 v253, 0xffff0000, v192
	v_fma_f32 v254, v130, v240, v154
	v_fma_f32 v255, v131, v241, v155
	v_fma_f32 v254, v138, v242, v254
	v_fma_f32 v255, v139, v243, v255
	v_fma_f32 v254, v146, v252, v254
	v_fma_f32 v255, v147, v253, v255
	v_mul_f32_e32 v240, 0xbfb8aa3b, v254
	v_mul_f32_e32 v241, 0xbfb8aa3b, v255
	v_exp_f32_e32 v240, v240
	v_exp_f32_e32 v241, v241
	v_add_f32_e32 v240, 1.0, v240
	v_add_f32_e32 v241, 1.0, v241
	v_rcp_f32_e32 v240, v240
	v_rcp_f32_e32 v241, v241
	v_mul_f32_e32 v254, v254, v240
	v_mul_f32_e32 v255, v255, v241
	v_mul_f32_e32 v254, v254, v78
	v_mul_f32_e32 v255, v255, v79
	v_cvt_pk_bf16_f32 v244, v254, v255
	v_lshlrev_b32_e32 v240, 16, v185
	v_and_b32_e32 v241, 0xffff0000, v185
	v_lshlrev_b32_e32 v242, 16, v189
	v_and_b32_e32 v243, 0xffff0000, v189
	v_lshlrev_b32_e32 v252, 16, v193
	v_and_b32_e32 v253, 0xffff0000, v193
	v_fma_f32 v254, v132, v240, v156
	v_fma_f32 v255, v133, v241, v157
	v_fma_f32 v254, v140, v242, v254
	v_fma_f32 v255, v141, v243, v255
	v_fma_f32 v254, v148, v252, v254
	v_fma_f32 v255, v149, v253, v255
	v_mul_f32_e32 v240, 0xbfb8aa3b, v254
	v_mul_f32_e32 v241, 0xbfb8aa3b, v255
	v_exp_f32_e32 v240, v240
	v_exp_f32_e32 v241, v241
	v_add_f32_e32 v240, 1.0, v240
	v_add_f32_e32 v241, 1.0, v241
	v_rcp_f32_e32 v240, v240
	v_rcp_f32_e32 v241, v241
	v_mul_f32_e32 v254, v254, v240
	v_mul_f32_e32 v255, v255, v241
	v_mul_f32_e32 v254, v254, v80
	v_mul_f32_e32 v255, v255, v81
	v_cvt_pk_bf16_f32 v245, v254, v255
	v_lshlrev_b32_e32 v240, 16, v186
	v_and_b32_e32 v241, 0xffff0000, v186
	v_lshlrev_b32_e32 v242, 16, v190
	v_and_b32_e32 v243, 0xffff0000, v190
	v_lshlrev_b32_e32 v252, 16, v194
	v_and_b32_e32 v253, 0xffff0000, v194
	v_fma_f32 v254, v134, v240, v158
	v_fma_f32 v255, v135, v241, v159
	v_fma_f32 v254, v142, v242, v254
	v_fma_f32 v255, v143, v243, v255
	v_fma_f32 v254, v150, v252, v254
	v_fma_f32 v255, v151, v253, v255
	v_mul_f32_e32 v240, 0xbfb8aa3b, v254
	v_mul_f32_e32 v241, 0xbfb8aa3b, v255
	v_exp_f32_e32 v240, v240
	v_exp_f32_e32 v241, v241
	v_add_f32_e32 v240, 1.0, v240
	v_add_f32_e32 v241, 1.0, v241
	v_rcp_f32_e32 v240, v240
	v_rcp_f32_e32 v241, v241
	v_mul_f32_e32 v254, v254, v240
	v_mul_f32_e32 v255, v255, v241
	v_mul_f32_e32 v254, v254, v74
	v_mul_f32_e32 v255, v255, v75
	v_cvt_pk_bf16_f32 v246, v254, v255
	v_lshlrev_b32_e32 v240, 16, v187
	v_and_b32_e32 v241, 0xffff0000, v187
	v_lshlrev_b32_e32 v242, 16, v191
	v_and_b32_e32 v243, 0xffff0000, v191
	v_lshlrev_b32_e32 v252, 16, v195
	v_and_b32_e32 v253, 0xffff0000, v195
	v_fma_f32 v254, v136, v240, v160
	v_fma_f32 v255, v137, v241, v161
	v_fma_f32 v254, v144, v242, v254
	v_fma_f32 v255, v145, v243, v255
	v_fma_f32 v254, v152, v252, v254
	v_fma_f32 v255, v153, v253, v255
	v_mul_f32_e32 v240, 0xbfb8aa3b, v254
	v_mul_f32_e32 v241, 0xbfb8aa3b, v255
	v_exp_f32_e32 v240, v240
	v_exp_f32_e32 v241, v241
	v_add_f32_e32 v240, 1.0, v240
	v_add_f32_e32 v241, 1.0, v241
	v_rcp_f32_e32 v240, v240
	v_rcp_f32_e32 v241, v241
	v_mul_f32_e32 v254, v254, v240
	v_mul_f32_e32 v255, v255, v241
	v_mul_f32_e32 v254, v254, v76
	v_mul_f32_e32 v255, v255, v77
	v_cvt_pk_bf16_f32 v247, v254, v255
	global_store_dwordx4 v[196:197], v[244:247], off offset:256
	v_add_u32_e32 v183, 0x7f, v176
	v_mad_i64_i32 v[222:223], s[0:1], v183, s14, v[180:181]
	v_lshl_add_u64 v[224:225], v[222:223], 0, s[98:99]
	v_lshl_add_u64 v[226:227], v[224:225], 0, s[98:99]
	v_lshl_add_u64 v[196:197], v[224:225], 0, s[100:101]
	global_load_dwordx4 v[184:187], v[222:223], off offset:256
	global_load_dwordx4 v[188:191], v[224:225], off offset:256
	global_load_dwordx4 v[192:195], v[226:227], off offset:256
	s_waitcnt vmcnt(4)
	v_lshlrev_b32_e32 v240, 16, v198
	v_and_b32_e32 v241, 0xffff0000, v198
	v_lshlrev_b32_e32 v242, 16, v202
	v_and_b32_e32 v243, 0xffff0000, v202
	v_lshlrev_b32_e32 v252, 16, v206
	v_and_b32_e32 v253, 0xffff0000, v206
	v_fma_f32 v254, v130, v240, v154
	v_fma_f32 v255, v131, v241, v155
	v_fma_f32 v254, v138, v242, v254
	v_fma_f32 v255, v139, v243, v255
	v_fma_f32 v254, v146, v252, v254
	v_fma_f32 v255, v147, v253, v255
	v_mul_f32_e32 v240, 0xbfb8aa3b, v254
	v_mul_f32_e32 v241, 0xbfb8aa3b, v255
	v_exp_f32_e32 v240, v240
	v_exp_f32_e32 v241, v241
	v_add_f32_e32 v240, 1.0, v240
	v_add_f32_e32 v241, 1.0, v241
	v_rcp_f32_e32 v240, v240
	v_rcp_f32_e32 v241, v241
	v_mul_f32_e32 v254, v254, v240
	v_mul_f32_e32 v255, v255, v241
	v_mul_f32_e32 v254, v254, v70
	v_mul_f32_e32 v255, v255, v71
	v_cvt_pk_bf16_f32 v248, v254, v255
	v_lshlrev_b32_e32 v240, 16, v199
	v_and_b32_e32 v241, 0xffff0000, v199
	v_lshlrev_b32_e32 v242, 16, v203
	v_and_b32_e32 v243, 0xffff0000, v203
	v_lshlrev_b32_e32 v252, 16, v207
	v_and_b32_e32 v253, 0xffff0000, v207
	v_fma_f32 v254, v132, v240, v156
	v_fma_f32 v255, v133, v241, v157
	v_fma_f32 v254, v140, v242, v254
	v_fma_f32 v255, v141, v243, v255
	v_fma_f32 v254, v148, v252, v254
	v_fma_f32 v255, v149, v253, v255
	v_mul_f32_e32 v240, 0xbfb8aa3b, v254
	v_mul_f32_e32 v241, 0xbfb8aa3b, v255
	v_exp_f32_e32 v240, v240
	v_exp_f32_e32 v241, v241
	v_add_f32_e32 v240, 1.0, v240
	v_add_f32_e32 v241, 1.0, v241
	v_rcp_f32_e32 v240, v240
	v_rcp_f32_e32 v241, v241
	v_mul_f32_e32 v254, v254, v240
	v_mul_f32_e32 v255, v255, v241
	v_mul_f32_e32 v254, v254, v72
	v_mul_f32_e32 v255, v255, v73
	v_cvt_pk_bf16_f32 v249, v254, v255
	v_lshlrev_b32_e32 v240, 16, v200
	v_and_b32_e32 v241, 0xffff0000, v200
	v_lshlrev_b32_e32 v242, 16, v204
	v_and_b32_e32 v243, 0xffff0000, v204
	v_lshlrev_b32_e32 v252, 16, v208
; DI unsigned pack2(float a, float b) { f32x2_t v = {a, b}; bf16x2_t r = __builtin_convertvector(v, bf16x2_t); return __builtin_bit_cast(unsigned, r); }
; DI float lo2f(unsigned u) { return __uint_as_float(u << 16); }
; DI float hi2f(unsigned u) { return __uint_as_float(u & 0xffff0000u); }
; DI float sigmoidf_(float x) { return __builtin_amdgcn_rcpf(1.f + __builtin_amdgcn_exp2f(-1.4426950408889634f * x)); }
;   DI void operator()(const f32x4 (&acc)[2][2][4][2], const pg8::Unit& u, int wr, int wc, int fr, int fq) const {
;     ...
;     } else {
; #pragma unroll
;       for (int ai = 0; ai < 2; ++ai) {
;         uint4 gs[4][2];
; #pragma unroll
;         for (int m = 0; m < 4; ++m)
; #pragma unroll
;           for (int bj = 0; bj < 2; ++bj)
;             gs[m][bj] = *(const uint4*)(o0 + (size_t)(row0 + ai * 128 + m * 16) * DFF + col0 + bj * 128);
;         __builtin_amdgcn_sched_barrier(0);
; #pragma unroll
;         for (int m = 0; m < 4; ++m)
; #pragma unroll
;           for (int bj = 0; bj < 2; ++bj) {
;             const f32x4 v0 = acc[ai][bj][m][0], v1 = acc[ai][bj][m][1];
;             const uint4 g = gs[m][bj];
;             f32x4 q0 = {lo2f(g.x) * v0[0], hi2f(g.x) * v0[1], lo2f(g.y) * v0[2], hi2f(g.y) * v0[3]};
;             f32x4 q1 = {lo2f(g.z) * v1[0], hi2f(g.z) * v1[1], lo2f(g.w) * v1[2], hi2f(g.w) * v1[3]};
;             st8(o0 + (size_t)(row0 + ai * 128 + m * 16) * DFF + col0 + bj * 128, q0, q1);
;           }
;         __builtin_amdgcn_sched_barrier(0);
;       }
; DI void conv_phase(const Params& p, int l) {
;     ...
;     for (int i = 0; i < RUN; ++i) {
;       unpack8(rows[i + 2], nxt);
;       float o[8];
; #pragma unroll
;       for (int j = 0; j < 8; ++j) { const float g = w0[j] * prev[j] + w1[j] * cur[j] + w2[j] * nxt[j] + bb[j]; o[j] = g * sigmoidf_(g); }
;       uint4 oo; oo.x = pack2(o[0], o[1]); oo.y = pack2(o[2], o[3]); oo.z = pack2(o[4], o[5]); oo.w = pack2(o[6], o[7]);
;       *(uint4*)(GS + (size_t)(t0 + i) * DFF + c0) = oo;
	v_and_b32_e32 v253, 0xffff0000, v208
	v_fma_f32 v254, v134, v240, v158
	v_fma_f32 v255, v135, v241, v159
	v_fma_f32 v254, v142, v242, v254
	v_fma_f32 v255, v143, v243, v255
	v_fma_f32 v254, v150, v252, v254
	v_fma_f32 v255, v151, v253, v255
	v_mul_f32_e32 v240, 0xbfb8aa3b, v254
	v_mul_f32_e32 v241, 0xbfb8aa3b, v255
	v_exp_f32_e32 v240, v240
	v_exp_f32_e32 v241, v241
	v_add_f32_e32 v240, 1.0, v240
	v_add_f32_e32 v241, 1.0, v241
	v_rcp_f32_e32 v240, v240
	v_rcp_f32_e32 v241, v241
	v_mul_f32_e32 v254, v254, v240
	v_mul_f32_e32 v255, v255, v241
	v_mul_f32_e32 v254, v254, v66
	v_mul_f32_e32 v255, v255, v67
	v_cvt_pk_bf16_f32 v250, v254, v255
	v_lshlrev_b32_e32 v240, 16, v201
	v_and_b32_e32 v241, 0xffff0000, v201
	v_lshlrev_b32_e32 v242, 16, v205
	v_and_b32_e32 v243, 0xffff0000, v205
	v_lshlrev_b32_e32 v252, 16, v209
	v_and_b32_e32 v253, 0xffff0000, v209
	v_fma_f32 v254, v136, v240, v160
	v_fma_f32 v255, v137, v241, v161
	v_fma_f32 v254, v144, v242, v254
	v_fma_f32 v255, v145, v243, v255
	v_fma_f32 v254, v152, v252, v254
	v_fma_f32 v255, v153, v253, v255
	v_mul_f32_e32 v240, 0xbfb8aa3b, v254
	v_mul_f32_e32 v241, 0xbfb8aa3b, v255
	v_exp_f32_e32 v240, v240
	v_exp_f32_e32 v241, v241
	v_add_f32_e32 v240, 1.0, v240
	v_add_f32_e32 v241, 1.0, v241
	v_rcp_f32_e32 v240, v240
	v_rcp_f32_e32 v241, v241
	v_mul_f32_e32 v254, v254, v240
	v_mul_f32_e32 v255, v255, v241
	v_mul_f32_e32 v254, v254, v68
	v_mul_f32_e32 v255, v255, v69
	v_cvt_pk_bf16_f32 v251, v254, v255
	global_store_dwordx4 v[220:221], v[248:251], off offset:256
	v_add_u32_e32 v183, 0x8f, v176
	v_mad_i64_i32 v[222:223], s[0:1], v183, s14, v[180:181]
	v_lshl_add_u64 v[224:225], v[222:223], 0, s[98:99]
	v_lshl_add_u64 v[226:227], v[224:225], 0, s[98:99]
	v_lshl_add_u64 v[220:221], v[224:225], 0, s[100:101]
	global_load_dwordx4 v[198:201], v[222:223], off offset:256
	global_load_dwordx4 v[202:205], v[224:225], off offset:256
	global_load_dwordx4 v[206:209], v[226:227], off offset:256
	s_waitcnt vmcnt(4)
	v_lshlrev_b32_e32 v240, 16, v184
	v_and_b32_e32 v241, 0xffff0000, v184
	v_lshlrev_b32_e32 v242, 16, v188
	v_and_b32_e32 v243, 0xffff0000, v188
	v_lshlrev_b32_e32 v252, 16, v192
	v_and_b32_e32 v253, 0xffff0000, v192
	v_fma_f32 v254, v130, v240, v154
	v_fma_f32 v255, v131, v241, v155
	v_fma_f32 v254, v138, v242, v254
	v_fma_f32 v255, v139, v243, v255
	v_fma_f32 v254, v146, v252, v254
	v_fma_f32 v255, v147, v253, v255
	v_mul_f32_e32 v240, 0xbfb8aa3b, v254
	v_mul_f32_e32 v241, 0xbfb8aa3b, v255
	v_exp_f32_e32 v240, v240
	v_exp_f32_e32 v241, v241
	v_add_f32_e32 v240, 1.0, v240
	v_add_f32_e32 v241, 1.0, v241
	v_rcp_f32_e32 v240, v240
	v_rcp_f32_e32 v241, v241
	v_mul_f32_e32 v254, v254, v240
	v_mul_f32_e32 v255, v255, v241
	v_mul_f32_e32 v254, v254, v46
	v_mul_f32_e32 v255, v255, v47
	v_cvt_pk_bf16_f32 v244, v254, v255
	v_lshlrev_b32_e32 v240, 16, v185
	v_and_b32_e32 v241, 0xffff0000, v185
	v_lshlrev_b32_e32 v242, 16, v189
	v_and_b32_e32 v243, 0xffff0000, v189
	v_lshlrev_b32_e32 v252, 16, v193
	v_and_b32_e32 v253, 0xffff0000, v193
	v_fma_f32 v254, v132, v240, v156
	v_fma_f32 v255, v133, v241, v157
	v_fma_f32 v254, v140, v242, v254
	v_fma_f32 v255, v141, v243, v255
	v_fma_f32 v254, v148, v252, v254
	v_fma_f32 v255, v149, v253, v255
	v_mul_f32_e32 v240, 0xbfb8aa3b, v254
	v_mul_f32_e32 v241, 0xbfb8aa3b, v255
	v_exp_f32_e32 v240, v240
	v_exp_f32_e32 v241, v241
	v_add_f32_e32 v240, 1.0, v240
	v_add_f32_e32 v241, 1.0, v241
	v_rcp_f32_e32 v240, v240
	v_rcp_f32_e32 v241, v241
	v_mul_f32_e32 v254, v254, v240
	v_mul_f32_e32 v255, v255, v241
	v_mul_f32_e32 v254, v254, v48
	v_mul_f32_e32 v255, v255, v49
	v_cvt_pk_bf16_f32 v245, v254, v255
	v_lshlrev_b32_e32 v240, 16, v186
	v_and_b32_e32 v241, 0xffff0000, v186
	v_lshlrev_b32_e32 v242, 16, v190
	v_and_b32_e32 v243, 0xffff0000, v190
	v_lshlrev_b32_e32 v252, 16, v194
	v_and_b32_e32 v253, 0xffff0000, v194
	v_fma_f32 v254, v134, v240, v158
	v_fma_f32 v255, v135, v241, v159
	v_fma_f32 v254, v142, v242, v254
	v_fma_f32 v255, v143, v243, v255
	v_fma_f32 v254, v150, v252, v254
	v_fma_f32 v255, v151, v253, v255
	v_mul_f32_e32 v240, 0xbfb8aa3b, v254
	v_mul_f32_e32 v241, 0xbfb8aa3b, v255
	v_exp_f32_e32 v240, v240
	v_exp_f32_e32 v241, v241
	v_add_f32_e32 v240, 1.0, v240
	v_add_f32_e32 v241, 1.0, v241
	v_rcp_f32_e32 v240, v240
	v_rcp_f32_e32 v241, v241
	v_mul_f32_e32 v254, v254, v240
	v_mul_f32_e32 v255, v255, v241
	v_mul_f32_e32 v254, v254, v42
	v_mul_f32_e32 v255, v255, v43
	v_cvt_pk_bf16_f32 v246, v254, v255
	v_lshlrev_b32_e32 v240, 16, v187
	v_and_b32_e32 v241, 0xffff0000, v187
	v_lshlrev_b32_e32 v242, 16, v191
	v_and_b32_e32 v243, 0xffff0000, v191
	v_lshlrev_b32_e32 v252, 16, v195
	v_and_b32_e32 v253, 0xffff0000, v195
	v_fma_f32 v254, v136, v240, v160
	v_fma_f32 v255, v137, v241, v161
	v_fma_f32 v254, v144, v242, v254
	v_fma_f32 v255, v145, v243, v255
	v_fma_f32 v254, v152, v252, v254
	v_fma_f32 v255, v153, v253, v255
	v_mul_f32_e32 v240, 0xbfb8aa3b, v254
	v_mul_f32_e32 v241, 0xbfb8aa3b, v255
	v_exp_f32_e32 v240, v240
	v_exp_f32_e32 v241, v241
	v_add_f32_e32 v240, 1.0, v240
	v_add_f32_e32 v241, 1.0, v241
	v_rcp_f32_e32 v240, v240
	v_rcp_f32_e32 v241, v241
	v_mul_f32_e32 v254, v254, v240
	v_mul_f32_e32 v255, v255, v241
	v_mul_f32_e32 v254, v254, v44
	v_mul_f32_e32 v255, v255, v45
	v_cvt_pk_bf16_f32 v247, v254, v255
	global_store_dwordx4 v[196:197], v[244:247], off offset:256
	v_add_u32_e32 v183, 0x9f, v176
	v_mad_i64_i32 v[222:223], s[0:1], v183, s14, v[180:181]
	v_lshl_add_u64 v[224:225], v[222:223], 0, s[98:99]
	v_lshl_add_u64 v[226:227], v[224:225], 0, s[98:99]
	v_lshl_add_u64 v[196:197], v[224:225], 0, s[100:101]
	global_load_dwordx4 v[184:187], v[222:223], off offset:256
	global_load_dwordx4 v[188:191], v[224:225], off offset:256
	global_load_dwordx4 v[192:195], v[226:227], off offset:256
	s_waitcnt vmcnt(4)
; DI unsigned pack2(float a, float b) { f32x2_t v = {a, b}; bf16x2_t r = __builtin_convertvector(v, bf16x2_t); return __builtin_bit_cast(unsigned, r); }
; DI float lo2f(unsigned u) { return __uint_as_float(u << 16); }
; DI float hi2f(unsigned u) { return __uint_as_float(u & 0xffff0000u); }
; DI float sigmoidf_(float x) { return __builtin_amdgcn_rcpf(1.f + __builtin_amdgcn_exp2f(-1.4426950408889634f * x)); }
;   DI void operator()(const f32x4 (&acc)[2][2][4][2], const pg8::Unit& u, int wr, int wc, int fr, int fq) const {
;     ...
;     } else {
; #pragma unroll
;       for (int ai = 0; ai < 2; ++ai) {
;         uint4 gs[4][2];
; #pragma unroll
;         for (int m = 0; m < 4; ++m)
; #pragma unroll
;           for (int bj = 0; bj < 2; ++bj)
;             gs[m][bj] = *(const uint4*)(o0 + (size_t)(row0 + ai * 128 + m * 16) * DFF + col0 + bj * 128);
;         __builtin_amdgcn_sched_barrier(0);
; #pragma unroll
;         for (int m = 0; m < 4; ++m)
; #pragma unroll
;           for (int bj = 0; bj < 2; ++bj) {
;             const f32x4 v0 = acc[ai][bj][m][0], v1 = acc[ai][bj][m][1];
;             const uint4 g = gs[m][bj];
;             f32x4 q0 = {lo2f(g.x) * v0[0], hi2f(g.x) * v0[1], lo2f(g.y) * v0[2], hi2f(g.y) * v0[3]};
;             f32x4 q1 = {lo2f(g.z) * v1[0], hi2f(g.z) * v1[1], lo2f(g.w) * v1[2], hi2f(g.w) * v1[3]};
;             st8(o0 + (size_t)(row0 + ai * 128 + m * 16) * DFF + col0 + bj * 128, q0, q1);
;           }
;         __builtin_amdgcn_sched_barrier(0);
;       }
; DI void conv_phase(const Params& p, int l) {
;     ...
;     for (int i = 0; i < RUN; ++i) {
;       unpack8(rows[i + 2], nxt);
;       float o[8];
; #pragma unroll
;       for (int j = 0; j < 8; ++j) { const float g = w0[j] * prev[j] + w1[j] * cur[j] + w2[j] * nxt[j] + bb[j]; o[j] = g * sigmoidf_(g); }
;       uint4 oo; oo.x = pack2(o[0], o[1]); oo.y = pack2(o[2], o[3]); oo.z = pack2(o[4], o[5]); oo.w = pack2(o[6], o[7]);
;       *(uint4*)(GS + (size_t)(t0 + i) * DFF + c0) = oo;
	v_lshlrev_b32_e32 v240, 16, v198
	v_and_b32_e32 v241, 0xffff0000, v198
	v_lshlrev_b32_e32 v242, 16, v202
	v_and_b32_e32 v243, 0xffff0000, v202
	v_lshlrev_b32_e32 v252, 16, v206
	v_and_b32_e32 v253, 0xffff0000, v206
	v_fma_f32 v254, v130, v240, v154
	v_fma_f32 v255, v131, v241, v155
	v_fma_f32 v254, v138, v242, v254
	v_fma_f32 v255, v139, v243, v255
	v_fma_f32 v254, v146, v252, v254
	v_fma_f32 v255, v147, v253, v255
	v_mul_f32_e32 v240, 0xbfb8aa3b, v254
	v_mul_f32_e32 v241, 0xbfb8aa3b, v255
	v_exp_f32_e32 v240, v240
	v_exp_f32_e32 v241, v241
	v_add_f32_e32 v240, 1.0, v240
	v_add_f32_e32 v241, 1.0, v241
	v_rcp_f32_e32 v240, v240
	v_rcp_f32_e32 v241, v241
	v_mul_f32_e32 v254, v254, v240
	v_mul_f32_e32 v255, v255, v241
	v_mul_f32_e32 v254, v254, v30
	v_mul_f32_e32 v255, v255, v31
	v_cvt_pk_bf16_f32 v248, v254, v255
	v_lshlrev_b32_e32 v240, 16, v199
	v_and_b32_e32 v241, 0xffff0000, v199
	v_lshlrev_b32_e32 v242, 16, v203
	v_and_b32_e32 v243, 0xffff0000, v203
	v_lshlrev_b32_e32 v252, 16, v207
	v_and_b32_e32 v253, 0xffff0000, v207
	v_fma_f32 v254, v132, v240, v156
	v_fma_f32 v255, v133, v241, v157
	v_fma_f32 v254, v140, v242, v254
	v_fma_f32 v255, v141, v243, v255
	v_fma_f32 v254, v148, v252, v254
	v_fma_f32 v255, v149, v253, v255
	v_mul_f32_e32 v240, 0xbfb8aa3b, v254
	v_mul_f32_e32 v241, 0xbfb8aa3b, v255
	v_exp_f32_e32 v240, v240
	v_exp_f32_e32 v241, v241
	v_add_f32_e32 v240, 1.0, v240
	v_add_f32_e32 v241, 1.0, v241
	v_rcp_f32_e32 v240, v240
	v_rcp_f32_e32 v241, v241
	v_mul_f32_e32 v254, v254, v240
	v_mul_f32_e32 v255, v255, v241
	v_mul_f32_e32 v254, v254, v32
	v_mul_f32_e32 v255, v255, v33
	v_cvt_pk_bf16_f32 v249, v254, v255
	v_lshlrev_b32_e32 v240, 16, v200
	v_and_b32_e32 v241, 0xffff0000, v200
	v_lshlrev_b32_e32 v242, 16, v204
	v_and_b32_e32 v243, 0xffff0000, v204
	v_lshlrev_b32_e32 v252, 16, v208
	v_and_b32_e32 v253, 0xffff0000, v208
	v_fma_f32 v254, v134, v240, v158
	v_fma_f32 v255, v135, v241, v159
	v_fma_f32 v254, v142, v242, v254
	v_fma_f32 v255, v143, v243, v255
	v_fma_f32 v254, v150, v252, v254
	v_fma_f32 v255, v151, v253, v255
	v_mul_f32_e32 v240, 0xbfb8aa3b, v254
	v_mul_f32_e32 v241, 0xbfb8aa3b, v255
	v_exp_f32_e32 v240, v240
	v_exp_f32_e32 v241, v241
	v_add_f32_e32 v240, 1.0, v240
	v_add_f32_e32 v241, 1.0, v241
	v_rcp_f32_e32 v240, v240
	v_rcp_f32_e32 v241, v241
	v_mul_f32_e32 v254, v254, v240
	v_mul_f32_e32 v255, v255, v241
	v_mul_f32_e32 v254, v254, v26
	v_mul_f32_e32 v255, v255, v27
	v_cvt_pk_bf16_f32 v250, v254, v255
	v_lshlrev_b32_e32 v240, 16, v201
	v_and_b32_e32 v241, 0xffff0000, v201
	v_lshlrev_b32_e32 v242, 16, v205
	v_and_b32_e32 v243, 0xffff0000, v205
	v_lshlrev_b32_e32 v252, 16, v209
	v_and_b32_e32 v253, 0xffff0000, v209
	v_fma_f32 v254, v136, v240, v160
	v_fma_f32 v255, v137, v241, v161
	v_fma_f32 v254, v144, v242, v254
	v_fma_f32 v255, v145, v243, v255
	v_fma_f32 v254, v152, v252, v254
	v_fma_f32 v255, v153, v253, v255
	v_mul_f32_e32 v240, 0xbfb8aa3b, v254
	v_mul_f32_e32 v241, 0xbfb8aa3b, v255
	v_exp_f32_e32 v240, v240
	v_exp_f32_e32 v241, v241
	v_add_f32_e32 v240, 1.0, v240
	v_add_f32_e32 v241, 1.0, v241
	v_rcp_f32_e32 v240, v240
	v_rcp_f32_e32 v241, v241
	v_mul_f32_e32 v254, v254, v240
	v_mul_f32_e32 v255, v255, v241
	v_mul_f32_e32 v254, v254, v28
	v_mul_f32_e32 v255, v255, v29
	v_cvt_pk_bf16_f32 v251, v254, v255
	global_store_dwordx4 v[220:221], v[248:251], off offset:256
	v_add_u32_e32 v183, 0xaf, v176
	v_mad_i64_i32 v[222:223], s[0:1], v183, s14, v[180:181]
	v_lshl_add_u64 v[224:225], v[222:223], 0, s[98:99]
	v_lshl_add_u64 v[226:227], v[224:225], 0, s[98:99]
	v_lshl_add_u64 v[220:221], v[224:225], 0, s[100:101]
	global_load_dwordx4 v[198:201], v[222:223], off offset:256
	global_load_dwordx4 v[202:205], v[224:225], off offset:256
	global_load_dwordx4 v[206:209], v[226:227], off offset:256
	s_waitcnt vmcnt(4)
; DI unsigned pack2(float a, float b) { f32x2_t v = {a, b}; bf16x2_t r = __builtin_convertvector(v, bf16x2_t); return __builtin_bit_cast(unsigned, r); }
; DI float lo2f(unsigned u) { return __uint_as_float(u << 16); }
; DI float hi2f(unsigned u) { return __uint_as_float(u & 0xffff0000u); }
; DI float sigmoidf_(float x) { return __builtin_amdgcn_rcpf(1.f + __builtin_amdgcn_exp2f(-1.4426950408889634f * x)); }
;   DI void operator()(const f32x4 (&acc)[2][2][4][2], const pg8::Unit& u, int wr, int wc, int fr, int fq) const {
;     ...
;     } else {
; #pragma unroll
;       for (int ai = 0; ai < 2; ++ai) {
;         uint4 gs[4][2];
; #pragma unroll
;         for (int m = 0; m < 4; ++m)
; #pragma unroll
;           for (int bj = 0; bj < 2; ++bj)
;             gs[m][bj] = *(const uint4*)(o0 + (size_t)(row0 + ai * 128 + m * 16) * DFF + col0 + bj * 128);
;         __builtin_amdgcn_sched_barrier(0);
; #pragma unroll
;         for (int m = 0; m < 4; ++m)
; #pragma unroll
;           for (int bj = 0; bj < 2; ++bj) {
;             const f32x4 v0 = acc[ai][bj][m][0], v1 = acc[ai][bj][m][1];
;             const uint4 g = gs[m][bj];
;             f32x4 q0 = {lo2f(g.x) * v0[0], hi2f(g.x) * v0[1], lo2f(g.y) * v0[2], hi2f(g.y) * v0[3]};
;             f32x4 q1 = {lo2f(g.z) * v1[0], hi2f(g.z) * v1[1], lo2f(g.w) * v1[2], hi2f(g.w) * v1[3]};
;             st8(o0 + (size_t)(row0 + ai * 128 + m * 16) * DFF + col0 + bj * 128, q0, q1);
;           }
;         __builtin_amdgcn_sched_barrier(0);
;       }
; DI void conv_phase(const Params& p, int l) {
;     ...
;     rows[RUN + 1] = (s0 + RUN - 1 < S - 1) ? *(const uint4*)(gp + (size_t)RUN * DFF) : z;
;     float w0[8], w1[8], w2[8], bb[8];
;     load8f(cw + c0, w0); load8f(cw + DFF + c0, w1); load8f(cw + 2 * DFF + c0, w2); load8f(cb + c0, bb);
;     float prev[8], cur[8], nxt[8];
;     unpack8(rows[0], prev); unpack8(rows[1], cur);
; #pragma unroll
;     for (int i = 0; i < RUN; ++i) {
;       unpack8(rows[i + 2], nxt);
;       float o[8];
; #pragma unroll
;       for (int j = 0; j < 8; ++j) { const float g = w0[j] * prev[j] + w1[j] * cur[j] + w2[j] * nxt[j] + bb[j]; o[j] = g * sigmoidf_(g); }
;       uint4 oo; oo.x = pack2(o[0], o[1]); oo.y = pack2(o[2], o[3]); oo.z = pack2(o[4], o[5]); oo.w = pack2(o[6], o[7]);
;       *(uint4*)(GS + (size_t)(t0 + i) * DFF + c0) = oo;
	v_lshlrev_b32_e32 v240, 16, v184
	v_and_b32_e32 v241, 0xffff0000, v184
	v_lshlrev_b32_e32 v242, 16, v188
	v_and_b32_e32 v243, 0xffff0000, v188
	v_lshlrev_b32_e32 v252, 16, v192
	v_and_b32_e32 v253, 0xffff0000, v192
	v_fma_f32 v254, v130, v240, v154
	v_fma_f32 v255, v131, v241, v155
	v_fma_f32 v254, v138, v242, v254
	v_fma_f32 v255, v139, v243, v255
	v_fma_f32 v254, v146, v252, v254
	v_fma_f32 v255, v147, v253, v255
	v_mul_f32_e32 v240, 0xbfb8aa3b, v254
	v_mul_f32_e32 v241, 0xbfb8aa3b, v255
	v_exp_f32_e32 v240, v240
	v_exp_f32_e32 v241, v241
	v_add_f32_e32 v240, 1.0, v240
	v_add_f32_e32 v241, 1.0, v241
	v_rcp_f32_e32 v240, v240
	v_rcp_f32_e32 v241, v241
	v_mul_f32_e32 v254, v254, v240
	v_mul_f32_e32 v255, v255, v241
	v_mul_f32_e32 v254, v254, v14
	v_mul_f32_e32 v255, v255, v15
	v_cvt_pk_bf16_f32 v244, v254, v255
	v_lshlrev_b32_e32 v240, 16, v185
	v_and_b32_e32 v241, 0xffff0000, v185
	v_lshlrev_b32_e32 v242, 16, v189
	v_and_b32_e32 v243, 0xffff0000, v189
	v_lshlrev_b32_e32 v252, 16, v193
	v_and_b32_e32 v253, 0xffff0000, v193
	v_fma_f32 v254, v132, v240, v156
	v_fma_f32 v255, v133, v241, v157
	v_fma_f32 v254, v140, v242, v254
	v_fma_f32 v255, v141, v243, v255
	v_fma_f32 v254, v148, v252, v254
	v_fma_f32 v255, v149, v253, v255
	v_mul_f32_e32 v240, 0xbfb8aa3b, v254
	v_mul_f32_e32 v241, 0xbfb8aa3b, v255
	v_exp_f32_e32 v240, v240
	v_exp_f32_e32 v241, v241
	v_add_f32_e32 v240, 1.0, v240
	v_add_f32_e32 v241, 1.0, v241
	v_rcp_f32_e32 v240, v240
	v_rcp_f32_e32 v241, v241
	v_mul_f32_e32 v254, v254, v240
	v_mul_f32_e32 v255, v255, v241
	v_mul_f32_e32 v254, v254, v16
	v_mul_f32_e32 v255, v255, v17
	v_cvt_pk_bf16_f32 v245, v254, v255
	v_lshlrev_b32_e32 v240, 16, v186
	v_and_b32_e32 v241, 0xffff0000, v186
	v_lshlrev_b32_e32 v242, 16, v190
	v_and_b32_e32 v243, 0xffff0000, v190
	v_lshlrev_b32_e32 v252, 16, v194
	v_and_b32_e32 v253, 0xffff0000, v194
	v_fma_f32 v254, v134, v240, v158
	v_fma_f32 v255, v135, v241, v159
	v_fma_f32 v254, v142, v242, v254
	v_fma_f32 v255, v143, v243, v255
	v_fma_f32 v254, v150, v252, v254
	v_fma_f32 v255, v151, v253, v255
	v_mul_f32_e32 v240, 0xbfb8aa3b, v254
	v_mul_f32_e32 v241, 0xbfb8aa3b, v255
	v_exp_f32_e32 v240, v240
	v_exp_f32_e32 v241, v241
	v_add_f32_e32 v240, 1.0, v240
	v_add_f32_e32 v241, 1.0, v241
	v_rcp_f32_e32 v240, v240
	v_rcp_f32_e32 v241, v241
	v_mul_f32_e32 v254, v254, v240
	v_mul_f32_e32 v255, v255, v241
	v_mul_f32_e32 v254, v254, v10
	v_mul_f32_e32 v255, v255, v11
	v_cvt_pk_bf16_f32 v246, v254, v255
	v_lshlrev_b32_e32 v240, 16, v187
	v_and_b32_e32 v241, 0xffff0000, v187
	v_lshlrev_b32_e32 v242, 16, v191
	v_and_b32_e32 v243, 0xffff0000, v191
	v_lshlrev_b32_e32 v252, 16, v195
	v_and_b32_e32 v253, 0xffff0000, v195
	v_fma_f32 v254, v136, v240, v160
	v_fma_f32 v255, v137, v241, v161
	v_fma_f32 v254, v144, v242, v254
	v_fma_f32 v255, v145, v243, v255
	v_fma_f32 v254, v152, v252, v254
	v_fma_f32 v255, v153, v253, v255
	v_mul_f32_e32 v240, 0xbfb8aa3b, v254
	v_mul_f32_e32 v241, 0xbfb8aa3b, v255
	v_exp_f32_e32 v240, v240
	v_exp_f32_e32 v241, v241
	v_add_f32_e32 v240, 1.0, v240
	v_add_f32_e32 v241, 1.0, v241
	v_rcp_f32_e32 v240, v240
	v_rcp_f32_e32 v241, v241
	v_mul_f32_e32 v254, v254, v240
	v_mul_f32_e32 v255, v255, v241
	v_mul_f32_e32 v254, v254, v12
	v_mul_f32_e32 v255, v255, v13
	v_cvt_pk_bf16_f32 v247, v254, v255
	global_store_dwordx4 v[196:197], v[244:247], off offset:256
	s_waitcnt vmcnt(1)
	v_add_u32_e32 v183, 0xb0, v176
	v_and_b32_e32 v183, 0x1fff, v183
	v_cmp_eq_u32_e32 vcc, 0x1fff, v183
	v_cndmask_b32_e64 v206, v206, 0, vcc
	v_cndmask_b32_e64 v207, v207, 0, vcc
	v_cndmask_b32_e64 v208, v208, 0, vcc
	v_cndmask_b32_e64 v209, v209, 0, vcc
	v_lshlrev_b32_e32 v240, 16, v198
	v_and_b32_e32 v241, 0xffff0000, v198
	v_lshlrev_b32_e32 v242, 16, v202
	v_and_b32_e32 v243, 0xffff0000, v202
	v_lshlrev_b32_e32 v252, 16, v206
	v_and_b32_e32 v253, 0xffff0000, v206
	v_fma_f32 v254, v130, v240, v154
	v_fma_f32 v255, v131, v241, v155
	v_fma_f32 v254, v138, v242, v254
	v_fma_f32 v255, v139, v243, v255
	v_fma_f32 v254, v146, v252, v254
	v_fma_f32 v255, v147, v253, v255
	v_mul_f32_e32 v240, 0xbfb8aa3b, v254
	v_mul_f32_e32 v241, 0xbfb8aa3b, v255
	v_exp_f32_e32 v240, v240
	v_exp_f32_e32 v241, v241
	v_add_f32_e32 v240, 1.0, v240
	v_add_f32_e32 v241, 1.0, v241
	v_rcp_f32_e32 v240, v240
	v_rcp_f32_e32 v241, v241
	v_mul_f32_e32 v254, v254, v240
	v_mul_f32_e32 v255, v255, v241
	v_mul_f32_e32 v254, v254, v6
	v_mul_f32_e32 v255, v255, v7
	v_cvt_pk_bf16_f32 v248, v254, v255
	v_lshlrev_b32_e32 v240, 16, v199
	v_and_b32_e32 v241, 0xffff0000, v199
	v_lshlrev_b32_e32 v242, 16, v203
	v_and_b32_e32 v243, 0xffff0000, v203
	v_lshlrev_b32_e32 v252, 16, v207
	v_and_b32_e32 v253, 0xffff0000, v207
	v_fma_f32 v254, v132, v240, v156
	v_fma_f32 v255, v133, v241, v157
	v_fma_f32 v254, v140, v242, v254
	v_fma_f32 v255, v141, v243, v255
	v_fma_f32 v254, v148, v252, v254
	v_fma_f32 v255, v149, v253, v255
	v_mul_f32_e32 v240, 0xbfb8aa3b, v254
	v_mul_f32_e32 v241, 0xbfb8aa3b, v255
	v_exp_f32_e32 v240, v240
	v_exp_f32_e32 v241, v241
	v_add_f32_e32 v240, 1.0, v240
	v_add_f32_e32 v241, 1.0, v241
	v_rcp_f32_e32 v240, v240
	v_rcp_f32_e32 v241, v241
	v_mul_f32_e32 v254, v254, v240
	v_mul_f32_e32 v255, v255, v241
	v_mul_f32_e32 v254, v254, v8
	v_mul_f32_e32 v255, v255, v9
	v_cvt_pk_bf16_f32 v249, v254, v255
	v_lshlrev_b32_e32 v240, 16, v200
	v_and_b32_e32 v241, 0xffff0000, v200
	v_lshlrev_b32_e32 v242, 16, v204
	v_and_b32_e32 v243, 0xffff0000, v204
	v_lshlrev_b32_e32 v252, 16, v208
	v_and_b32_e32 v253, 0xffff0000, v208
	v_fma_f32 v254, v134, v240, v158
	v_fma_f32 v255, v135, v241, v159
	v_fma_f32 v254, v142, v242, v254
	v_fma_f32 v255, v143, v243, v255
	v_fma_f32 v254, v150, v252, v254
	v_fma_f32 v255, v151, v253, v255
	v_mul_f32_e32 v240, 0xbfb8aa3b, v254
	v_mul_f32_e32 v241, 0xbfb8aa3b, v255
	v_exp_f32_e32 v240, v240
	v_exp_f32_e32 v241, v241
	v_add_f32_e32 v240, 1.0, v240
	v_add_f32_e32 v241, 1.0, v241
	v_rcp_f32_e32 v240, v240
	v_rcp_f32_e32 v241, v241
	v_mul_f32_e32 v254, v254, v240
	v_mul_f32_e32 v255, v255, v241
	v_mul_f32_e32 v254, v254, v2
	v_mul_f32_e32 v255, v255, v3
	v_cvt_pk_bf16_f32 v250, v254, v255
	v_lshlrev_b32_e32 v240, 16, v201
	v_and_b32_e32 v241, 0xffff0000, v201
	v_lshlrev_b32_e32 v242, 16, v205
	v_and_b32_e32 v243, 0xffff0000, v205
	v_lshlrev_b32_e32 v252, 16, v209
	v_and_b32_e32 v253, 0xffff0000, v209
	v_fma_f32 v254, v136, v240, v160
	v_fma_f32 v255, v137, v241, v161
	v_fma_f32 v254, v144, v242, v254
	v_fma_f32 v255, v145, v243, v255
	v_fma_f32 v254, v152, v252, v254
	v_fma_f32 v255, v153, v253, v255
	v_mul_f32_e32 v240, 0xbfb8aa3b, v254
	v_mul_f32_e32 v241, 0xbfb8aa3b, v255
	v_exp_f32_e32 v240, v240
	v_exp_f32_e32 v241, v241
	v_add_f32_e32 v240, 1.0, v240
	v_add_f32_e32 v241, 1.0, v241
	v_rcp_f32_e32 v240, v240
	v_rcp_f32_e32 v241, v241
	v_mul_f32_e32 v254, v254, v240
	v_mul_f32_e32 v255, v255, v241
	v_mul_f32_e32 v254, v254, v4
	v_mul_f32_e32 v255, v255, v5
	v_cvt_pk_bf16_f32 v251, v254, v255
	global_store_dwordx4 v[220:221], v[248:251], off offset:256
	s_mov_b64 s[0:1], 0

; #define PG8_WAIT_V(n) asm volatile("s_waitcnt vmcnt(" #n ")" ::: "memory")
; #define PG8_BAR __builtin_amdgcn_s_barrier()
; template <class Epi, class Sched, bool STAMP = false>
; __device__ __forceinline__ void gemm_phase(PG8_LAS unsigned char* lds, const Gemm g, const Sched& S, const Epi& E, unsigned long long* stamps) {
;     ...
;     PG8_WAIT_V(0);
;     if (wr == 0) PG8_BAR;
;     PG8_BAR;
.LBB0_1033:
	s_setprio 0
	s_waitcnt vmcnt(0)
	v_readlane_b32 s80, v237, 58
	v_readlane_b32 s88, v237, 52
	s_cmpk_gt_u32 s76, 0xff
	v_readlane_b32 s81, v237, 59
	v_readlane_b32 s89, v237, 53
	v_readlane_b32 s90, v237, 54
	v_readlane_b32 s91, v237, 55
	v_readlane_b32 s92, v237, 56
	v_readlane_b32 s34, v237, 57
	v_readlane_b32 s33, v237, 62
	s_cbranch_scc1 .LBB0_1035
	s_barrier
